# GEMM K-loop edge edits (7.11 in miniature): loop-carried scalar bookkeeping moved into the last MFMA cluster's shadow, next-stage pointer selects moved below the A-fragment LDS reads; five K-loops
# baseline (speedup 1.0000x reference)
;     __host__ __device__ bool next(int i, Unit& u) const { if (i) return false; u.pm = pm; u.pn = pn; return true; }
; #define PG8_STAGE(bufoff, gbase, voff) do { _Pragma("unroll") for (int _i = 0; _i < 2; ++_i) \
;         __builtin_amdgcn_global_load_lds((const unsigned*)((const char*)(gbase) + (voff)[_i]), (PG8_LAS unsigned*)(lds + (bufoff) + ldsw + _i * 8192), 16, 0, 0); } while (0)
; #define PG8_LDA(dst, b, h) do { _Pragma("unroll") for (int m = 0; m < 4; ++m) _Pragma("unroll") for (int k = 0; k < 2; ++k) dst[m][k] = *(const PG8_LAS bf16x8*)(lds + PG8_SA(b, h) + aoff + m * 2048 + k * 1024); } while (0)
; #define PG8_LDB(dst, b, h) do { _Pragma("unroll") for (int n = 0; n < 2; ++n) _Pragma("unroll") for (int k = 0; k < 2; ++k) dst[n][k] = *(const PG8_LAS bf16x8*)(lds + PG8_SB(b, h) + boff + n * 2048 + k * 1024); } while (0)
; #define PG8_WAIT_V(n) asm volatile("s_waitcnt vmcnt(" #n ")" ::: "memory")
; #define PG8_WAIT_L(n) asm volatile("s_waitcnt lgkmcnt(" #n ")" ::: "memory")
; template <class Epi, class Sched, bool ALIGN_EPI = false, bool SP2 = false>
; __device__ __forceinline__ void gemm_phase(PG8_LAS unsigned char* lds, const Gemm g, const Sched& S, const Epi& E) {
;     ...
;         const bool has_next = S.next(ui + 1, nxt);
;         const char* nA = has_next ? (const char*)g.A + (size_t)nxt.pm * tstep : cA; const char* nB = has_next ? (const char*)g.Bt + (size_t)nxt.pn * tstep : cB;
;         for (int t = 0; t < nt; t += 2) {
;             const bool last = (t == nt - 2);
;             const char* a1 = cA + (size_t)(t + 1) * kstep;
;             const char* a2 = last ? nA : cA + (size_t)(t + 2) * kstep; const char* b2 = last ? nB : cB + (size_t)(t + 2) * kstep;
;             const char* a3 = a2 + kstep; const char* b3 = b2 + kstep;
;             if (last && has_next) S.a_ready(nxt);
;             if constexpr (SP2) {
;             PG8_LDB(B0, 0, 0); PG8_LDB(B1, 0, 1); PG8_SCHED; PG8_LDA(At, 0, 0); PG8_STAGE(PG8_SA(1, 1), a1 + hstep, voffA);
;             PG8_WAIT_V(8); PG8_WAIT_L(0); PG8_BAR; PG8_MMA(0, 0, At, B0); PG8_MMA(0, 1, At, B1); PG8_BAR; PG8_SCHED;
;             PG8_LDA(At, 0, 1); PG8_STAGE(PG8_SB(0, 0), b2, voffB); PG8_STAGE(PG8_SB(0, 1), b2 + hstep, voffB); PG8_STAGE(PG8_SA(0, 0), a2, voffA);
;             PG8_WAIT_V(8); PG8_WAIT_L(0); PG8_BAR; PG8_MMA(1, 0, At, B0); PG8_MMA(1, 1, At, B1); PG8_BAR; PG8_SCHED;
.LBB0_279:
	s_add_i32 s69, 0, 0x10000
	v_add_u32_e32 v142, s69, v145
	s_add_i32 s72, 0, 0x14000
	ds_read_b128 v[148:151], v142
	ds_read_b128 v[152:155], v142 offset:1024
	ds_read_b128 v[156:159], v142 offset:2048
	ds_read_b128 v[160:163], v142 offset:3072
	v_add_u32_e32 v142, s72, v145
	ds_read_b128 v[172:175], v142
	ds_read_b128 v[176:179], v142 offset:1024
	ds_read_b128 v[180:183], v142 offset:2048
	ds_read_b128 v[184:187], v142 offset:3072
	s_add_u32 s48, s46, 0xfff00080
	s_addc_u32 s49, s47, -1
	s_cmp_eq_u32 s68, 60
	s_cselect_b32 s51, s37, s49
	s_cselect_b32 s50, s64, s48
	s_cselect_b32 s49, s9, s67
	s_cselect_b32 s48, s65, s66
	v_lshl_add_u64 v[142:143], s[46:47], 0, v[138:139]
	s_add_i32 m0, s43, 0xc000
	ds_read_b128 v[206:209], v147
	ds_read_b128 v[210:213], v147 offset:1024
	ds_read_b128 v[214:217], v147 offset:2048
	ds_read_b128 v[218:221], v147 offset:3072
	ds_read_b128 v[222:225], v147 offset:4096
	ds_read_b128 v[226:229], v147 offset:5120
	ds_read_b128 v[230:233], v147 offset:6144
	ds_read_b128 v[234:237], v147 offset:7168
	global_load_lds_dwordx4 v[142:143], off
	v_lshl_add_u64 v[142:143], s[46:47], 0, v[140:141]
	s_add_i32 m0, s43, 0xe000
	s_nop 0
	global_load_lds_dwordx4 v[142:143], off
	s_waitcnt vmcnt(8)
	s_waitcnt lgkmcnt(0)
	s_barrier
	s_setprio 1
	s_waitcnt lgkmcnt(0)
	v_mfma_f32_16x16x32_bf16 v[128:131], v[148:151], v[206:209], v[128:131]
	v_mfma_f32_16x16x32_bf16 v[124:127], v[156:159], v[206:209], v[124:127]
	v_mfma_f32_16x16x32_bf16 v[120:123], v[148:151], v[214:217], v[120:123]
	v_mfma_f32_16x16x32_bf16 v[112:115], v[156:159], v[214:217], v[112:115]
	v_mfma_f32_16x16x32_bf16 v[104:107], v[148:151], v[222:225], v[104:107]
	v_mfma_f32_16x16x32_bf16 v[96:99], v[156:159], v[222:225], v[96:99]
	v_mfma_f32_16x16x32_bf16 v[88:91], v[148:151], v[230:233], v[88:91]
	v_mfma_f32_16x16x32_bf16 v[80:83], v[156:159], v[230:233], v[80:83]
	v_mfma_f32_16x16x32_bf16 v[128:131], v[152:155], v[210:213], v[128:131]
	v_mfma_f32_16x16x32_bf16 v[124:127], v[160:163], v[210:213], v[124:127]
	v_mfma_f32_16x16x32_bf16 v[120:123], v[152:155], v[218:221], v[120:123]
	v_mfma_f32_16x16x32_bf16 v[112:115], v[160:163], v[218:221], v[112:115]
	v_mfma_f32_16x16x32_bf16 v[104:107], v[152:155], v[226:229], v[104:107]
	v_mfma_f32_16x16x32_bf16 v[96:99], v[160:163], v[226:229], v[96:99]
	v_mfma_f32_16x16x32_bf16 v[88:91], v[152:155], v[234:237], v[88:91]
	v_mfma_f32_16x16x32_bf16 v[80:83], v[160:163], v[234:237], v[80:83]
	s_setprio 0
	s_setprio 1
	v_mfma_f32_16x16x32_bf16 v[116:119], v[172:175], v[206:209], v[116:119]
	v_mfma_f32_16x16x32_bf16 v[108:111], v[180:183], v[206:209], v[108:111]
	v_mfma_f32_16x16x32_bf16 v[100:103], v[172:175], v[214:217], v[100:103]
	v_mfma_f32_16x16x32_bf16 v[92:95], v[180:183], v[214:217], v[92:95]
	v_mfma_f32_16x16x32_bf16 v[84:87], v[172:175], v[222:225], v[84:87]
	v_mfma_f32_16x16x32_bf16 v[76:79], v[180:183], v[222:225], v[76:79]
	v_mfma_f32_16x16x32_bf16 v[72:75], v[172:175], v[230:233], v[72:75]
	v_mfma_f32_16x16x32_bf16 v[68:71], v[180:183], v[230:233], v[68:71]
	v_mfma_f32_16x16x32_bf16 v[116:119], v[176:179], v[210:213], v[116:119]
	v_mfma_f32_16x16x32_bf16 v[108:111], v[184:187], v[210:213], v[108:111]
	v_mfma_f32_16x16x32_bf16 v[100:103], v[176:179], v[218:221], v[100:103]
	v_mfma_f32_16x16x32_bf16 v[92:95], v[184:187], v[218:221], v[92:95]
	v_mfma_f32_16x16x32_bf16 v[84:87], v[176:179], v[226:229], v[84:87]
	v_mfma_f32_16x16x32_bf16 v[76:79], v[184:187], v[226:229], v[76:79]
	v_mfma_f32_16x16x32_bf16 v[72:75], v[176:179], v[234:237], v[72:75]
	v_mfma_f32_16x16x32_bf16 v[68:71], v[184:187], v[234:237], v[68:71]
	s_setprio 0
	s_barrier
	s_add_i32 s69, s69, s56
	v_lshl_add_u64 v[142:143], s[48:49], 0, v[2:3]
	s_mov_b32 m0, s69
	ds_read_b128 v[206:209], v147 offset:16384
	ds_read_b128 v[210:213], v147 offset:17408
	ds_read_b128 v[214:217], v147 offset:18432
	ds_read_b128 v[218:221], v147 offset:19456
	ds_read_b128 v[222:225], v147 offset:20480
	ds_read_b128 v[226:229], v147 offset:21504
	ds_read_b128 v[230:233], v147 offset:22528
	ds_read_b128 v[234:237], v147 offset:23552
	global_load_lds_dwordx4 v[142:143], off
	s_add_i32 m0, s69, 0x2000
	s_add_u32 s70, s48, 0x100000
	v_lshl_add_u64 v[164:165], s[48:49], 0, v[136:137]
	s_addc_u32 s71, s49, 0
	s_add_i32 s69, s72, s56
	global_load_lds_dwordx4 v[164:165], off
	v_lshl_add_u64 v[238:239], s[70:71], 0, v[2:3]
	s_mov_b32 m0, s69
	v_lshl_add_u64 v[240:241], s[50:51], 0, v[134:135]
	global_load_lds_dwordx4 v[238:239], off
	v_lshl_add_u64 v[238:239], s[70:71], 0, v[136:137]
	s_add_i32 m0, s69, 0x2000
	s_nop 0
	global_load_lds_dwordx4 v[238:239], off
	v_lshl_add_u64 v[238:239], s[50:51], 0, v[132:133]
	s_mov_b32 m0, s43
	s_nop 0
	global_load_lds_dwordx4 v[238:239], off
	s_mov_b32 m0, s57
	s_nop 0
	global_load_lds_dwordx4 v[240:241], off
	s_waitcnt vmcnt(8)
	s_waitcnt lgkmcnt(0)
	s_barrier
; #define PG8_STAGE(bufoff, gbase, voff) do { _Pragma("unroll") for (int _i = 0; _i < 2; ++_i) \
;         __builtin_amdgcn_global_load_lds((const unsigned*)((const char*)(gbase) + (voff)[_i]), (PG8_LAS unsigned*)(lds + (bufoff) + ldsw + _i * 8192), 16, 0, 0); } while (0)
; #define PG8_LDA(dst, b, h) do { _Pragma("unroll") for (int m = 0; m < 4; ++m) _Pragma("unroll") for (int k = 0; k < 2; ++k) dst[m][k] = *(const PG8_LAS bf16x8*)(lds + PG8_SA(b, h) + aoff + m * 2048 + k * 1024); } while (0)
; #define PG8_LDB(dst, b, h) do { _Pragma("unroll") for (int n = 0; n < 2; ++n) _Pragma("unroll") for (int k = 0; k < 2; ++k) dst[n][k] = *(const PG8_LAS bf16x8*)(lds + PG8_SB(b, h) + boff + n * 2048 + k * 1024); } while (0)
; #define PG8_MMA(ai, bj, At, Bt) do { __builtin_amdgcn_s_setprio(1); _Pragma("unroll") for (int m = 0; m < 4; ++m) _Pragma("unroll") for (int n = 0; n < 2; ++n) _Pragma("unroll") for (int k = 0; k < 2; ++k) \
;         acc[ai][bj][m][n] = __builtin_amdgcn_mfma_f32_16x16x32_bf16(Bt[n][k], At[m][k], acc[ai][bj][m][n], 0, 0, 0); __builtin_amdgcn_s_setprio(0); } while (0)
; #define PG8_WAIT_V(n) asm volatile("s_waitcnt vmcnt(" #n ")" ::: "memory")
; #define PG8_WAIT_L(n) asm volatile("s_waitcnt lgkmcnt(" #n ")" ::: "memory")
; #define PG8_BAR __builtin_amdgcn_s_barrier()
; #define PG8_SCHED __builtin_amdgcn_sched_barrier(0)
; template <class Epi, class Sched, bool ALIGN_EPI = false, bool SP2 = false>
; __device__ __forceinline__ void gemm_phase(PG8_LAS unsigned char* lds, const Gemm g, const Sched& S, const Epi& E) {
;     ...
;             PG8_WAIT_V(8); PG8_WAIT_L(0); PG8_BAR; PG8_MMA(1, 0, At, B0); PG8_MMA(1, 1, At, B1); PG8_BAR; PG8_SCHED;
;             PG8_LDB(B0, 1, 0); PG8_LDB(B1, 1, 1); PG8_SCHED; PG8_LDA(At, 1, 0); PG8_STAGE(PG8_SA(0, 1), a2 + hstep, voffA);
;             PG8_WAIT_V(8); PG8_WAIT_L(0); PG8_BAR; PG8_MMA(0, 0, At, B0); PG8_MMA(0, 1, At, B1); PG8_BAR; PG8_SCHED;
;             PG8_LDA(At, 1, 1); PG8_STAGE(PG8_SB(1, 0), b3, voffB); PG8_STAGE(PG8_SB(1, 1), b3 + hstep, voffB); PG8_STAGE(PG8_SA(1, 0), a3, voffA);
	s_setprio 1
	s_waitcnt lgkmcnt(0)
	v_mfma_f32_16x16x32_bf16 v[64:67], v[148:151], v[206:209], v[64:67]
	v_mfma_f32_16x16x32_bf16 v[60:63], v[156:159], v[206:209], v[60:63]
	v_mfma_f32_16x16x32_bf16 v[56:59], v[148:151], v[214:217], v[56:59]
	v_mfma_f32_16x16x32_bf16 v[48:51], v[156:159], v[214:217], v[48:51]
	v_mfma_f32_16x16x32_bf16 v[40:43], v[148:151], v[222:225], v[40:43]
	v_mfma_f32_16x16x32_bf16 v[32:35], v[156:159], v[222:225], v[32:35]
	v_mfma_f32_16x16x32_bf16 v[24:27], v[148:151], v[230:233], v[24:27]
	v_mfma_f32_16x16x32_bf16 v[16:19], v[156:159], v[230:233], v[16:19]
	v_mfma_f32_16x16x32_bf16 v[64:67], v[152:155], v[210:213], v[64:67]
	v_mfma_f32_16x16x32_bf16 v[60:63], v[160:163], v[210:213], v[60:63]
	v_mfma_f32_16x16x32_bf16 v[56:59], v[152:155], v[218:221], v[56:59]
	v_mfma_f32_16x16x32_bf16 v[48:51], v[160:163], v[218:221], v[48:51]
	v_mfma_f32_16x16x32_bf16 v[40:43], v[152:155], v[226:229], v[40:43]
	v_mfma_f32_16x16x32_bf16 v[32:35], v[160:163], v[226:229], v[32:35]
	v_mfma_f32_16x16x32_bf16 v[24:27], v[152:155], v[234:237], v[24:27]
	v_mfma_f32_16x16x32_bf16 v[16:19], v[160:163], v[234:237], v[16:19]
	s_setprio 0
	s_setprio 1
	v_mfma_f32_16x16x32_bf16 v[52:55], v[172:175], v[206:209], v[52:55]
	v_mfma_f32_16x16x32_bf16 v[44:47], v[180:183], v[206:209], v[44:47]
	v_mfma_f32_16x16x32_bf16 v[36:39], v[172:175], v[214:217], v[36:39]
	v_mfma_f32_16x16x32_bf16 v[28:31], v[180:183], v[214:217], v[28:31]
	v_mfma_f32_16x16x32_bf16 v[20:23], v[172:175], v[222:225], v[20:23]
	v_mfma_f32_16x16x32_bf16 v[12:15], v[180:183], v[222:225], v[12:15]
	v_mfma_f32_16x16x32_bf16 v[8:11], v[172:175], v[230:233], v[8:11]
	v_mfma_f32_16x16x32_bf16 v[4:7], v[180:183], v[230:233], v[4:7]
	v_mfma_f32_16x16x32_bf16 v[52:55], v[176:179], v[210:213], v[52:55]
	v_mfma_f32_16x16x32_bf16 v[44:47], v[184:187], v[210:213], v[44:47]
	v_mfma_f32_16x16x32_bf16 v[36:39], v[176:179], v[218:221], v[36:39]
	v_mfma_f32_16x16x32_bf16 v[28:31], v[184:187], v[218:221], v[28:31]
	v_mfma_f32_16x16x32_bf16 v[20:23], v[176:179], v[226:229], v[20:23]
	v_mfma_f32_16x16x32_bf16 v[12:15], v[184:187], v[226:229], v[12:15]
	v_mfma_f32_16x16x32_bf16 v[8:11], v[176:179], v[234:237], v[8:11]
	v_mfma_f32_16x16x32_bf16 v[4:7], v[184:187], v[234:237], v[4:7]
	s_setprio 0
	s_barrier
	s_add_i32 s69, 0, 0x18000
	s_add_i32 s70, 0, 0x1c000
	v_add_u32_e32 v160, s69, v145
	v_add_u32_e32 v184, s70, v145
	ds_read_b128 v[148:151], v160
	ds_read_b128 v[152:155], v160 offset:1024
	ds_read_b128 v[156:159], v160 offset:2048
	ds_read_b128 v[160:163], v160 offset:3072
	ds_read_b128 v[172:175], v184
	ds_read_b128 v[176:179], v184 offset:1024
	ds_read_b128 v[180:183], v184 offset:2048
	ds_read_b128 v[184:187], v184 offset:3072
	s_add_u32 s50, s50, 0x100000
	s_addc_u32 s51, s51, 0
	s_mov_b32 m0, s58
	v_lshl_add_u64 v[242:243], s[50:51], 0, v[132:133]
	ds_read_b128 v[206:209], v147 offset:32768
	ds_read_b128 v[210:213], v147 offset:33792
	ds_read_b128 v[214:217], v147 offset:34816
	ds_read_b128 v[218:221], v147 offset:35840
	ds_read_b128 v[222:225], v147 offset:36864
	ds_read_b128 v[226:229], v147 offset:37888
	ds_read_b128 v[230:233], v147 offset:38912
	ds_read_b128 v[234:237], v147 offset:39936
	global_load_lds_dwordx4 v[242:243], off
	v_lshl_add_u64 v[242:243], s[50:51], 0, v[134:135]
	s_mov_b32 m0, s59
	s_nop 0
	global_load_lds_dwordx4 v[242:243], off
	s_waitcnt vmcnt(8)
	s_waitcnt lgkmcnt(0)
	s_barrier
	s_setprio 1
	s_waitcnt lgkmcnt(0)
	v_mfma_f32_16x16x32_bf16 v[128:131], v[148:151], v[206:209], v[128:131]
	v_mfma_f32_16x16x32_bf16 v[124:127], v[156:159], v[206:209], v[124:127]
	v_mfma_f32_16x16x32_bf16 v[120:123], v[148:151], v[214:217], v[120:123]
	v_mfma_f32_16x16x32_bf16 v[112:115], v[156:159], v[214:217], v[112:115]
	v_mfma_f32_16x16x32_bf16 v[104:107], v[148:151], v[222:225], v[104:107]
	v_mfma_f32_16x16x32_bf16 v[96:99], v[156:159], v[222:225], v[96:99]
	v_mfma_f32_16x16x32_bf16 v[88:91], v[148:151], v[230:233], v[88:91]
	v_mfma_f32_16x16x32_bf16 v[80:83], v[156:159], v[230:233], v[80:83]
	v_mfma_f32_16x16x32_bf16 v[128:131], v[152:155], v[210:213], v[128:131]
	v_mfma_f32_16x16x32_bf16 v[124:127], v[160:163], v[210:213], v[124:127]
	v_mfma_f32_16x16x32_bf16 v[120:123], v[152:155], v[218:221], v[120:123]
	v_mfma_f32_16x16x32_bf16 v[112:115], v[160:163], v[218:221], v[112:115]
	v_mfma_f32_16x16x32_bf16 v[104:107], v[152:155], v[226:229], v[104:107]
	v_mfma_f32_16x16x32_bf16 v[96:99], v[160:163], v[226:229], v[96:99]
	v_mfma_f32_16x16x32_bf16 v[88:91], v[152:155], v[234:237], v[88:91]
	v_mfma_f32_16x16x32_bf16 v[80:83], v[160:163], v[234:237], v[80:83]
	s_setprio 0
	s_setprio 1
	v_mfma_f32_16x16x32_bf16 v[116:119], v[172:175], v[206:209], v[116:119]
	v_mfma_f32_16x16x32_bf16 v[108:111], v[180:183], v[206:209], v[108:111]
	v_mfma_f32_16x16x32_bf16 v[100:103], v[172:175], v[214:217], v[100:103]
	v_mfma_f32_16x16x32_bf16 v[92:95], v[180:183], v[214:217], v[92:95]
	v_mfma_f32_16x16x32_bf16 v[84:87], v[172:175], v[222:225], v[84:87]
	v_mfma_f32_16x16x32_bf16 v[76:79], v[180:183], v[222:225], v[76:79]
	v_mfma_f32_16x16x32_bf16 v[72:75], v[172:175], v[230:233], v[72:75]
	v_mfma_f32_16x16x32_bf16 v[68:71], v[180:183], v[230:233], v[68:71]
	v_mfma_f32_16x16x32_bf16 v[116:119], v[176:179], v[210:213], v[116:119]
	v_mfma_f32_16x16x32_bf16 v[108:111], v[184:187], v[210:213], v[108:111]
	v_mfma_f32_16x16x32_bf16 v[100:103], v[176:179], v[218:221], v[100:103]
	v_mfma_f32_16x16x32_bf16 v[92:95], v[184:187], v[218:221], v[92:95]
	v_mfma_f32_16x16x32_bf16 v[84:87], v[176:179], v[226:229], v[84:87]
	v_mfma_f32_16x16x32_bf16 v[76:79], v[184:187], v[226:229], v[76:79]
	v_mfma_f32_16x16x32_bf16 v[72:75], v[176:179], v[234:237], v[72:75]
	v_mfma_f32_16x16x32_bf16 v[68:71], v[184:187], v[234:237], v[68:71]
	s_setprio 0
	s_barrier
; #define PG8_STAGE(bufoff, gbase, voff) do { _Pragma("unroll") for (int _i = 0; _i < 2; ++_i) \
;         __builtin_amdgcn_global_load_lds((const unsigned*)((const char*)(gbase) + (voff)[_i]), (PG8_LAS unsigned*)(lds + (bufoff) + ldsw + _i * 8192), 16, 0, 0); } while (0)
; #define PG8_LDA(dst, b, h) do { _Pragma("unroll") for (int m = 0; m < 4; ++m) _Pragma("unroll") for (int k = 0; k < 2; ++k) dst[m][k] = *(const PG8_LAS bf16x8*)(lds + PG8_SA(b, h) + aoff + m * 2048 + k * 1024); } while (0)
; #define PG8_MMA(ai, bj, At, Bt) do { __builtin_amdgcn_s_setprio(1); _Pragma("unroll") for (int m = 0; m < 4; ++m) _Pragma("unroll") for (int n = 0; n < 2; ++n) _Pragma("unroll") for (int k = 0; k < 2; ++k) \
;         acc[ai][bj][m][n] = __builtin_amdgcn_mfma_f32_16x16x32_bf16(Bt[n][k], At[m][k], acc[ai][bj][m][n], 0, 0, 0); __builtin_amdgcn_s_setprio(0); } while (0)
; #define PG8_WAIT_V(n) asm volatile("s_waitcnt vmcnt(" #n ")" ::: "memory")
; #define PG8_WAIT_L(n) asm volatile("s_waitcnt lgkmcnt(" #n ")" ::: "memory")
; #define PG8_BAR __builtin_amdgcn_s_barrier()
; #define PG8_SCHED __builtin_amdgcn_sched_barrier(0)
; template <class Epi, class Sched, bool ALIGN_EPI = false, bool SP2 = false>
; __device__ __forceinline__ void gemm_phase(PG8_LAS unsigned char* lds, const Gemm g, const Sched& S, const Epi& E) {
;     ...
;         for (int t = 0; t < nt; t += 2) {
;     ...
;             PG8_LDA(At, 1, 1); PG8_STAGE(PG8_SB(1, 0), b3, voffB); PG8_STAGE(PG8_SB(1, 1), b3 + hstep, voffB); PG8_STAGE(PG8_SA(1, 0), a3, voffA);
;             PG8_WAIT_V(8); PG8_WAIT_L(0); PG8_BAR; PG8_MMA(1, 0, At, B0); PG8_MMA(1, 1, At, B1); PG8_BAR; PG8_SCHED;
	s_add_i32 s50, s69, s56
	v_lshl_add_u64 v[142:143], v[142:143], 0, s[28:29]
	s_mov_b32 m0, s50
	ds_read_b128 v[206:209], v147 offset:49152
	ds_read_b128 v[210:213], v147 offset:50176
	ds_read_b128 v[214:217], v147 offset:51200
	ds_read_b128 v[218:221], v147 offset:52224
	ds_read_b128 v[222:225], v147 offset:53248
	ds_read_b128 v[226:229], v147 offset:54272
	ds_read_b128 v[230:233], v147 offset:55296
	ds_read_b128 v[234:237], v147 offset:56320
	global_load_lds_dwordx4 v[142:143], off
	s_add_i32 m0, s50, 0x2000
	s_add_u32 s48, s48, 0x100080
	v_lshl_add_u64 v[142:143], v[164:165], 0, s[28:29]
	s_addc_u32 s49, s49, 0
	s_add_i32 s50, s70, s56
	global_load_lds_dwordx4 v[142:143], off
	v_lshl_add_u64 v[142:143], s[48:49], 0, v[2:3]
	s_mov_b32 m0, s50
	s_nop 0
	global_load_lds_dwordx4 v[142:143], off
	v_lshl_add_u64 v[142:143], s[48:49], 0, v[136:137]
	s_add_i32 m0, s50, 0x2000
	s_nop 0
	global_load_lds_dwordx4 v[142:143], off
	v_lshl_add_u64 v[142:143], v[238:239], 0, s[28:29]
	s_mov_b32 m0, s60
	s_nop 0
	global_load_lds_dwordx4 v[142:143], off
	v_lshl_add_u64 v[142:143], v[240:241], 0, s[28:29]
	s_mov_b32 m0, s61
	s_nop 0
	global_load_lds_dwordx4 v[142:143], off
	s_waitcnt vmcnt(8)
	s_waitcnt lgkmcnt(0)
	s_barrier
	s_setprio 1
	s_waitcnt lgkmcnt(0)
	v_mfma_f32_16x16x32_bf16 v[64:67], v[148:151], v[206:209], v[64:67]
	v_mfma_f32_16x16x32_bf16 v[60:63], v[156:159], v[206:209], v[60:63]
	v_mfma_f32_16x16x32_bf16 v[56:59], v[148:151], v[214:217], v[56:59]
	v_mfma_f32_16x16x32_bf16 v[48:51], v[156:159], v[214:217], v[48:51]
	v_mfma_f32_16x16x32_bf16 v[40:43], v[148:151], v[222:225], v[40:43]
	v_mfma_f32_16x16x32_bf16 v[32:35], v[156:159], v[222:225], v[32:35]
	v_mfma_f32_16x16x32_bf16 v[24:27], v[148:151], v[230:233], v[24:27]
	v_mfma_f32_16x16x32_bf16 v[16:19], v[156:159], v[230:233], v[16:19]
	v_mfma_f32_16x16x32_bf16 v[64:67], v[152:155], v[210:213], v[64:67]
	v_mfma_f32_16x16x32_bf16 v[60:63], v[160:163], v[210:213], v[60:63]
	v_mfma_f32_16x16x32_bf16 v[56:59], v[152:155], v[218:221], v[56:59]
	v_mfma_f32_16x16x32_bf16 v[48:51], v[160:163], v[218:221], v[48:51]
	v_mfma_f32_16x16x32_bf16 v[40:43], v[152:155], v[226:229], v[40:43]
	v_mfma_f32_16x16x32_bf16 v[32:35], v[160:163], v[226:229], v[32:35]
	v_mfma_f32_16x16x32_bf16 v[24:27], v[152:155], v[234:237], v[24:27]
	v_mfma_f32_16x16x32_bf16 v[16:19], v[160:163], v[234:237], v[16:19]
	s_setprio 0
	s_setprio 1
	v_mfma_f32_16x16x32_bf16 v[52:55], v[172:175], v[206:209], v[52:55]
	s_add_i32 s68, s68, 2
	s_add_u32 s46, s46, 0x100
	s_addc_u32 s47, s47, 0
	s_add_u32 s66, s66, 0x100
	s_addc_u32 s67, s67, 0
	s_cmp_gt_u32 s68, 61
	v_mfma_f32_16x16x32_bf16 v[44:47], v[180:183], v[206:209], v[44:47]
	v_mfma_f32_16x16x32_bf16 v[36:39], v[172:175], v[214:217], v[36:39]
	v_mfma_f32_16x16x32_bf16 v[28:31], v[180:183], v[214:217], v[28:31]
	v_mfma_f32_16x16x32_bf16 v[20:23], v[172:175], v[222:225], v[20:23]
	v_mfma_f32_16x16x32_bf16 v[12:15], v[180:183], v[222:225], v[12:15]
	v_mfma_f32_16x16x32_bf16 v[8:11], v[172:175], v[230:233], v[8:11]
	v_mfma_f32_16x16x32_bf16 v[4:7], v[180:183], v[230:233], v[4:7]
	v_mfma_f32_16x16x32_bf16 v[52:55], v[176:179], v[210:213], v[52:55]
	v_mfma_f32_16x16x32_bf16 v[44:47], v[184:187], v[210:213], v[44:47]
	v_mfma_f32_16x16x32_bf16 v[36:39], v[176:179], v[218:221], v[36:39]
	v_mfma_f32_16x16x32_bf16 v[28:31], v[184:187], v[218:221], v[28:31]
	v_mfma_f32_16x16x32_bf16 v[20:23], v[176:179], v[226:229], v[20:23]
	v_mfma_f32_16x16x32_bf16 v[12:15], v[184:187], v[226:229], v[12:15]
	v_mfma_f32_16x16x32_bf16 v[8:11], v[176:179], v[234:237], v[8:11]
	v_mfma_f32_16x16x32_bf16 v[4:7], v[184:187], v[234:237], v[4:7]
	s_setprio 0
	s_barrier
	s_cbranch_scc0 .LBB0_279
	s_and_b64 vcc, exec, s[6:7]
	s_cbranch_vccz .LBB0_282
	s_barrier

;     __host__ __device__ bool next(int i, Unit& u) const { if (i) return false; u.pm = pm; u.pn = pn; return true; }
; #define PG8_STAGE(bufoff, gbase, voff) do { _Pragma("unroll") for (int _i = 0; _i < 2; ++_i) \
;         __builtin_amdgcn_global_load_lds((const unsigned*)((const char*)(gbase) + (voff)[_i]), (PG8_LAS unsigned*)(lds + (bufoff) + ldsw + _i * 8192), 16, 0, 0); } while (0)
; #define PG8_LDA(dst, b, h) do { _Pragma("unroll") for (int m = 0; m < 4; ++m) _Pragma("unroll") for (int k = 0; k < 2; ++k) dst[m][k] = *(const PG8_LAS bf16x8*)(lds + PG8_SA(b, h) + aoff + m * 2048 + k * 1024); } while (0)
; #define PG8_LDB(dst, b, h) do { _Pragma("unroll") for (int n = 0; n < 2; ++n) _Pragma("unroll") for (int k = 0; k < 2; ++k) dst[n][k] = *(const PG8_LAS bf16x8*)(lds + PG8_SB(b, h) + boff + n * 2048 + k * 1024); } while (0)
; #define PG8_WAIT_V(n) asm volatile("s_waitcnt vmcnt(" #n ")" ::: "memory")
; #define PG8_WAIT_L(n) asm volatile("s_waitcnt lgkmcnt(" #n ")" ::: "memory")
; template <class Epi, class Sched, bool ALIGN_EPI = false, bool SP2 = false>
; __device__ __forceinline__ void gemm_phase(PG8_LAS unsigned char* lds, const Gemm g, const Sched& S, const Epi& E) {
;     ...
;         const bool has_next = S.next(ui + 1, nxt);
;         const char* nA = has_next ? (const char*)g.A + (size_t)nxt.pm * tstep : cA; const char* nB = has_next ? (const char*)g.Bt + (size_t)nxt.pn * tstep : cB;
;         for (int t = 0; t < nt; t += 2) {
;             const bool last = (t == nt - 2);
;             const char* a1 = cA + (size_t)(t + 1) * kstep;
;             const char* a2 = last ? nA : cA + (size_t)(t + 2) * kstep; const char* b2 = last ? nB : cB + (size_t)(t + 2) * kstep;
;             const char* a3 = a2 + kstep; const char* b3 = b2 + kstep;
;             if (last && has_next) S.a_ready(nxt);
;             if constexpr (SP2) {
;             PG8_LDB(B0, 0, 0); PG8_LDB(B1, 0, 1); PG8_SCHED; PG8_LDA(At, 0, 0); PG8_STAGE(PG8_SA(1, 1), a1 + hstep, voffA);
;             PG8_WAIT_V(8); PG8_WAIT_L(0); PG8_BAR; PG8_MMA(0, 0, At, B0); PG8_MMA(0, 1, At, B1); PG8_BAR; PG8_SCHED;
;             PG8_LDA(At, 0, 1); PG8_STAGE(PG8_SB(0, 0), b2, voffB); PG8_STAGE(PG8_SB(0, 1), b2 + hstep, voffB); PG8_STAGE(PG8_SA(0, 0), a2, voffA);
;             PG8_WAIT_V(8); PG8_WAIT_L(0); PG8_BAR; PG8_MMA(1, 0, At, B0); PG8_MMA(1, 1, At, B1); PG8_BAR; PG8_SCHED;
.LBB0_360:
	s_add_i32 s77, 0, 0x10000
	v_add_u32_e32 v142, s77, v145
	s_add_i32 s80, 0, 0x14000
	ds_read_b128 v[148:151], v142
	ds_read_b128 v[152:155], v142 offset:1024
	ds_read_b128 v[156:159], v142 offset:2048
	ds_read_b128 v[160:163], v142 offset:3072
	v_add_u32_e32 v142, s80, v145
	ds_read_b128 v[172:175], v142
	ds_read_b128 v[176:179], v142 offset:1024
	ds_read_b128 v[180:183], v142 offset:2048
	ds_read_b128 v[184:187], v142 offset:3072
	s_add_u32 s48, s46, 0xfff00080
	s_addc_u32 s49, s47, -1
	s_cmp_eq_u32 s76, 60
	s_cselect_b32 s51, s39, s49
	s_cselect_b32 s50, s72, s48
	s_cselect_b32 s49, s37, s75
	s_cselect_b32 s48, s73, s74
	v_lshl_add_u64 v[142:143], s[46:47], 0, v[138:139]
	s_add_i32 m0, s9, 0xc000
	ds_read_b128 v[206:209], v147
	ds_read_b128 v[210:213], v147 offset:1024
	ds_read_b128 v[214:217], v147 offset:2048
	ds_read_b128 v[218:221], v147 offset:3072
	ds_read_b128 v[222:225], v147 offset:4096
	ds_read_b128 v[226:229], v147 offset:5120
	ds_read_b128 v[230:233], v147 offset:6144
	ds_read_b128 v[234:237], v147 offset:7168
	global_load_lds_dwordx4 v[142:143], off
	v_lshl_add_u64 v[142:143], s[46:47], 0, v[140:141]
	s_add_i32 m0, s9, 0xe000
	s_nop 0
	global_load_lds_dwordx4 v[142:143], off
	s_waitcnt vmcnt(8)
	s_waitcnt lgkmcnt(0)
	s_barrier
	s_setprio 1
	s_waitcnt lgkmcnt(0)
	v_mfma_f32_16x16x32_bf16 v[128:131], v[148:151], v[206:209], v[128:131]
	v_mfma_f32_16x16x32_bf16 v[124:127], v[156:159], v[206:209], v[124:127]
	v_mfma_f32_16x16x32_bf16 v[120:123], v[148:151], v[214:217], v[120:123]
	v_mfma_f32_16x16x32_bf16 v[112:115], v[156:159], v[214:217], v[112:115]
	v_mfma_f32_16x16x32_bf16 v[104:107], v[148:151], v[222:225], v[104:107]
	v_mfma_f32_16x16x32_bf16 v[96:99], v[156:159], v[222:225], v[96:99]
	v_mfma_f32_16x16x32_bf16 v[88:91], v[148:151], v[230:233], v[88:91]
	v_mfma_f32_16x16x32_bf16 v[80:83], v[156:159], v[230:233], v[80:83]
	v_mfma_f32_16x16x32_bf16 v[128:131], v[152:155], v[210:213], v[128:131]
	v_mfma_f32_16x16x32_bf16 v[124:127], v[160:163], v[210:213], v[124:127]
	v_mfma_f32_16x16x32_bf16 v[120:123], v[152:155], v[218:221], v[120:123]
	v_mfma_f32_16x16x32_bf16 v[112:115], v[160:163], v[218:221], v[112:115]
	v_mfma_f32_16x16x32_bf16 v[104:107], v[152:155], v[226:229], v[104:107]
	v_mfma_f32_16x16x32_bf16 v[96:99], v[160:163], v[226:229], v[96:99]
	v_mfma_f32_16x16x32_bf16 v[88:91], v[152:155], v[234:237], v[88:91]
	v_mfma_f32_16x16x32_bf16 v[80:83], v[160:163], v[234:237], v[80:83]
	s_setprio 0
	s_setprio 1
	v_mfma_f32_16x16x32_bf16 v[116:119], v[172:175], v[206:209], v[116:119]
	v_mfma_f32_16x16x32_bf16 v[108:111], v[180:183], v[206:209], v[108:111]
	v_mfma_f32_16x16x32_bf16 v[100:103], v[172:175], v[214:217], v[100:103]
	v_mfma_f32_16x16x32_bf16 v[92:95], v[180:183], v[214:217], v[92:95]
	v_mfma_f32_16x16x32_bf16 v[84:87], v[172:175], v[222:225], v[84:87]
	v_mfma_f32_16x16x32_bf16 v[76:79], v[180:183], v[222:225], v[76:79]
	v_mfma_f32_16x16x32_bf16 v[72:75], v[172:175], v[230:233], v[72:75]
	v_mfma_f32_16x16x32_bf16 v[68:71], v[180:183], v[230:233], v[68:71]
	v_mfma_f32_16x16x32_bf16 v[116:119], v[176:179], v[210:213], v[116:119]
	v_mfma_f32_16x16x32_bf16 v[108:111], v[184:187], v[210:213], v[108:111]
	v_mfma_f32_16x16x32_bf16 v[100:103], v[176:179], v[218:221], v[100:103]
	v_mfma_f32_16x16x32_bf16 v[92:95], v[184:187], v[218:221], v[92:95]
	v_mfma_f32_16x16x32_bf16 v[84:87], v[176:179], v[226:229], v[84:87]
	v_mfma_f32_16x16x32_bf16 v[76:79], v[184:187], v[226:229], v[76:79]
	v_mfma_f32_16x16x32_bf16 v[72:75], v[176:179], v[234:237], v[72:75]
	v_mfma_f32_16x16x32_bf16 v[68:71], v[184:187], v[234:237], v[68:71]
	s_setprio 0
	s_barrier
	s_add_i32 s77, s77, s63
	v_lshl_add_u64 v[142:143], s[48:49], 0, v[2:3]
	s_mov_b32 m0, s77
	ds_read_b128 v[206:209], v147 offset:16384
	ds_read_b128 v[210:213], v147 offset:17408
	ds_read_b128 v[214:217], v147 offset:18432
	ds_read_b128 v[218:221], v147 offset:19456
	ds_read_b128 v[222:225], v147 offset:20480
	ds_read_b128 v[226:229], v147 offset:21504
	ds_read_b128 v[230:233], v147 offset:22528
	ds_read_b128 v[234:237], v147 offset:23552
	global_load_lds_dwordx4 v[142:143], off
	s_add_i32 m0, s77, 0x2000
	s_add_u32 s78, s48, 0x100000
	v_lshl_add_u64 v[164:165], s[48:49], 0, v[136:137]
	s_addc_u32 s79, s49, 0
	s_add_i32 s77, s80, s63
	global_load_lds_dwordx4 v[164:165], off
	v_lshl_add_u64 v[238:239], s[78:79], 0, v[2:3]
	s_mov_b32 m0, s77
	v_lshl_add_u64 v[240:241], s[50:51], 0, v[134:135]
	global_load_lds_dwordx4 v[238:239], off
	v_lshl_add_u64 v[238:239], s[78:79], 0, v[136:137]
	s_add_i32 m0, s77, 0x2000
	s_nop 0
	global_load_lds_dwordx4 v[238:239], off
	v_lshl_add_u64 v[238:239], s[50:51], 0, v[132:133]
	s_mov_b32 m0, s9
	s_nop 0
	global_load_lds_dwordx4 v[238:239], off
	s_mov_b32 m0, s64
	s_nop 0
	global_load_lds_dwordx4 v[240:241], off
	s_waitcnt vmcnt(8)
	s_waitcnt lgkmcnt(0)
	s_barrier
; #define PG8_STAGE(bufoff, gbase, voff) do { _Pragma("unroll") for (int _i = 0; _i < 2; ++_i) \
;         __builtin_amdgcn_global_load_lds((const unsigned*)((const char*)(gbase) + (voff)[_i]), (PG8_LAS unsigned*)(lds + (bufoff) + ldsw + _i * 8192), 16, 0, 0); } while (0)
; #define PG8_LDA(dst, b, h) do { _Pragma("unroll") for (int m = 0; m < 4; ++m) _Pragma("unroll") for (int k = 0; k < 2; ++k) dst[m][k] = *(const PG8_LAS bf16x8*)(lds + PG8_SA(b, h) + aoff + m * 2048 + k * 1024); } while (0)
; #define PG8_LDB(dst, b, h) do { _Pragma("unroll") for (int n = 0; n < 2; ++n) _Pragma("unroll") for (int k = 0; k < 2; ++k) dst[n][k] = *(const PG8_LAS bf16x8*)(lds + PG8_SB(b, h) + boff + n * 2048 + k * 1024); } while (0)
; #define PG8_MMA(ai, bj, At, Bt) do { __builtin_amdgcn_s_setprio(1); _Pragma("unroll") for (int m = 0; m < 4; ++m) _Pragma("unroll") for (int n = 0; n < 2; ++n) _Pragma("unroll") for (int k = 0; k < 2; ++k) \
;         acc[ai][bj][m][n] = __builtin_amdgcn_mfma_f32_16x16x32_bf16(Bt[n][k], At[m][k], acc[ai][bj][m][n], 0, 0, 0); __builtin_amdgcn_s_setprio(0); } while (0)
; #define PG8_WAIT_V(n) asm volatile("s_waitcnt vmcnt(" #n ")" ::: "memory")
; #define PG8_WAIT_L(n) asm volatile("s_waitcnt lgkmcnt(" #n ")" ::: "memory")
; #define PG8_BAR __builtin_amdgcn_s_barrier()
; #define PG8_SCHED __builtin_amdgcn_sched_barrier(0)
; template <class Epi, class Sched, bool ALIGN_EPI = false, bool SP2 = false>
; __device__ __forceinline__ void gemm_phase(PG8_LAS unsigned char* lds, const Gemm g, const Sched& S, const Epi& E) {
;     ...
;             PG8_WAIT_V(8); PG8_WAIT_L(0); PG8_BAR; PG8_MMA(1, 0, At, B0); PG8_MMA(1, 1, At, B1); PG8_BAR; PG8_SCHED;
;             PG8_LDB(B0, 1, 0); PG8_LDB(B1, 1, 1); PG8_SCHED; PG8_LDA(At, 1, 0); PG8_STAGE(PG8_SA(0, 1), a2 + hstep, voffA);
;             PG8_WAIT_V(8); PG8_WAIT_L(0); PG8_BAR; PG8_MMA(0, 0, At, B0); PG8_MMA(0, 1, At, B1); PG8_BAR; PG8_SCHED;
;             PG8_LDA(At, 1, 1); PG8_STAGE(PG8_SB(1, 0), b3, voffB); PG8_STAGE(PG8_SB(1, 1), b3 + hstep, voffB); PG8_STAGE(PG8_SA(1, 0), a3, voffA);
	s_setprio 1
	s_waitcnt lgkmcnt(0)
	v_mfma_f32_16x16x32_bf16 v[64:67], v[148:151], v[206:209], v[64:67]
	v_mfma_f32_16x16x32_bf16 v[60:63], v[156:159], v[206:209], v[60:63]
	v_mfma_f32_16x16x32_bf16 v[56:59], v[148:151], v[214:217], v[56:59]
	v_mfma_f32_16x16x32_bf16 v[48:51], v[156:159], v[214:217], v[48:51]
	v_mfma_f32_16x16x32_bf16 v[40:43], v[148:151], v[222:225], v[40:43]
	v_mfma_f32_16x16x32_bf16 v[32:35], v[156:159], v[222:225], v[32:35]
	v_mfma_f32_16x16x32_bf16 v[24:27], v[148:151], v[230:233], v[24:27]
	v_mfma_f32_16x16x32_bf16 v[16:19], v[156:159], v[230:233], v[16:19]
	v_mfma_f32_16x16x32_bf16 v[64:67], v[152:155], v[210:213], v[64:67]
	v_mfma_f32_16x16x32_bf16 v[60:63], v[160:163], v[210:213], v[60:63]
	v_mfma_f32_16x16x32_bf16 v[56:59], v[152:155], v[218:221], v[56:59]
	v_mfma_f32_16x16x32_bf16 v[48:51], v[160:163], v[218:221], v[48:51]
	v_mfma_f32_16x16x32_bf16 v[40:43], v[152:155], v[226:229], v[40:43]
	v_mfma_f32_16x16x32_bf16 v[32:35], v[160:163], v[226:229], v[32:35]
	v_mfma_f32_16x16x32_bf16 v[24:27], v[152:155], v[234:237], v[24:27]
	v_mfma_f32_16x16x32_bf16 v[16:19], v[160:163], v[234:237], v[16:19]
	s_setprio 0
	s_setprio 1
	v_mfma_f32_16x16x32_bf16 v[52:55], v[172:175], v[206:209], v[52:55]
	v_mfma_f32_16x16x32_bf16 v[44:47], v[180:183], v[206:209], v[44:47]
	v_mfma_f32_16x16x32_bf16 v[36:39], v[172:175], v[214:217], v[36:39]
	v_mfma_f32_16x16x32_bf16 v[28:31], v[180:183], v[214:217], v[28:31]
	v_mfma_f32_16x16x32_bf16 v[20:23], v[172:175], v[222:225], v[20:23]
	v_mfma_f32_16x16x32_bf16 v[12:15], v[180:183], v[222:225], v[12:15]
	v_mfma_f32_16x16x32_bf16 v[8:11], v[172:175], v[230:233], v[8:11]
	v_mfma_f32_16x16x32_bf16 v[4:7], v[180:183], v[230:233], v[4:7]
	v_mfma_f32_16x16x32_bf16 v[52:55], v[176:179], v[210:213], v[52:55]
	v_mfma_f32_16x16x32_bf16 v[44:47], v[184:187], v[210:213], v[44:47]
	v_mfma_f32_16x16x32_bf16 v[36:39], v[176:179], v[218:221], v[36:39]
	v_mfma_f32_16x16x32_bf16 v[28:31], v[184:187], v[218:221], v[28:31]
	v_mfma_f32_16x16x32_bf16 v[20:23], v[176:179], v[226:229], v[20:23]
	v_mfma_f32_16x16x32_bf16 v[12:15], v[184:187], v[226:229], v[12:15]
	v_mfma_f32_16x16x32_bf16 v[8:11], v[176:179], v[234:237], v[8:11]
	v_mfma_f32_16x16x32_bf16 v[4:7], v[184:187], v[234:237], v[4:7]
	s_setprio 0
	s_barrier
	s_add_i32 s77, 0, 0x18000
	s_add_i32 s78, 0, 0x1c000
	v_add_u32_e32 v160, s77, v145
	v_add_u32_e32 v184, s78, v145
	ds_read_b128 v[148:151], v160
	ds_read_b128 v[152:155], v160 offset:1024
	ds_read_b128 v[156:159], v160 offset:2048
	ds_read_b128 v[160:163], v160 offset:3072
	ds_read_b128 v[172:175], v184
	ds_read_b128 v[176:179], v184 offset:1024
	ds_read_b128 v[180:183], v184 offset:2048
	ds_read_b128 v[184:187], v184 offset:3072
	s_add_u32 s50, s50, 0x100000
	s_addc_u32 s51, s51, 0
	s_mov_b32 m0, s65
	v_lshl_add_u64 v[242:243], s[50:51], 0, v[132:133]
	ds_read_b128 v[206:209], v147 offset:32768
	ds_read_b128 v[210:213], v147 offset:33792
	ds_read_b128 v[214:217], v147 offset:34816
	ds_read_b128 v[218:221], v147 offset:35840
	ds_read_b128 v[222:225], v147 offset:36864
	ds_read_b128 v[226:229], v147 offset:37888
	ds_read_b128 v[230:233], v147 offset:38912
	ds_read_b128 v[234:237], v147 offset:39936
	global_load_lds_dwordx4 v[242:243], off
	v_lshl_add_u64 v[242:243], s[50:51], 0, v[134:135]
	s_mov_b32 m0, s66
	s_nop 0
	global_load_lds_dwordx4 v[242:243], off
	s_waitcnt vmcnt(8)
	s_waitcnt lgkmcnt(0)
	s_barrier
	s_setprio 1
	s_waitcnt lgkmcnt(0)
	v_mfma_f32_16x16x32_bf16 v[128:131], v[148:151], v[206:209], v[128:131]
	v_mfma_f32_16x16x32_bf16 v[124:127], v[156:159], v[206:209], v[124:127]
	v_mfma_f32_16x16x32_bf16 v[120:123], v[148:151], v[214:217], v[120:123]
	v_mfma_f32_16x16x32_bf16 v[112:115], v[156:159], v[214:217], v[112:115]
	v_mfma_f32_16x16x32_bf16 v[104:107], v[148:151], v[222:225], v[104:107]
	v_mfma_f32_16x16x32_bf16 v[96:99], v[156:159], v[222:225], v[96:99]
	v_mfma_f32_16x16x32_bf16 v[88:91], v[148:151], v[230:233], v[88:91]
	v_mfma_f32_16x16x32_bf16 v[80:83], v[156:159], v[230:233], v[80:83]
	v_mfma_f32_16x16x32_bf16 v[128:131], v[152:155], v[210:213], v[128:131]
	v_mfma_f32_16x16x32_bf16 v[124:127], v[160:163], v[210:213], v[124:127]
	v_mfma_f32_16x16x32_bf16 v[120:123], v[152:155], v[218:221], v[120:123]
	v_mfma_f32_16x16x32_bf16 v[112:115], v[160:163], v[218:221], v[112:115]
	v_mfma_f32_16x16x32_bf16 v[104:107], v[152:155], v[226:229], v[104:107]
	v_mfma_f32_16x16x32_bf16 v[96:99], v[160:163], v[226:229], v[96:99]
	v_mfma_f32_16x16x32_bf16 v[88:91], v[152:155], v[234:237], v[88:91]
	v_mfma_f32_16x16x32_bf16 v[80:83], v[160:163], v[234:237], v[80:83]
	s_setprio 0
	s_setprio 1
	v_mfma_f32_16x16x32_bf16 v[116:119], v[172:175], v[206:209], v[116:119]
	v_mfma_f32_16x16x32_bf16 v[108:111], v[180:183], v[206:209], v[108:111]
	v_mfma_f32_16x16x32_bf16 v[100:103], v[172:175], v[214:217], v[100:103]
	v_mfma_f32_16x16x32_bf16 v[92:95], v[180:183], v[214:217], v[92:95]
	v_mfma_f32_16x16x32_bf16 v[84:87], v[172:175], v[222:225], v[84:87]
	v_mfma_f32_16x16x32_bf16 v[76:79], v[180:183], v[222:225], v[76:79]
	v_mfma_f32_16x16x32_bf16 v[72:75], v[172:175], v[230:233], v[72:75]
	v_mfma_f32_16x16x32_bf16 v[68:71], v[180:183], v[230:233], v[68:71]
	v_mfma_f32_16x16x32_bf16 v[116:119], v[176:179], v[210:213], v[116:119]
	v_mfma_f32_16x16x32_bf16 v[108:111], v[184:187], v[210:213], v[108:111]
	v_mfma_f32_16x16x32_bf16 v[100:103], v[176:179], v[218:221], v[100:103]
	v_mfma_f32_16x16x32_bf16 v[92:95], v[184:187], v[218:221], v[92:95]
	v_mfma_f32_16x16x32_bf16 v[84:87], v[176:179], v[226:229], v[84:87]
	v_mfma_f32_16x16x32_bf16 v[76:79], v[184:187], v[226:229], v[76:79]
	v_mfma_f32_16x16x32_bf16 v[72:75], v[176:179], v[234:237], v[72:75]
	v_mfma_f32_16x16x32_bf16 v[68:71], v[184:187], v[234:237], v[68:71]
	s_setprio 0
	s_barrier
; #define PG8_STAGE(bufoff, gbase, voff) do { _Pragma("unroll") for (int _i = 0; _i < 2; ++_i) \
;         __builtin_amdgcn_global_load_lds((const unsigned*)((const char*)(gbase) + (voff)[_i]), (PG8_LAS unsigned*)(lds + (bufoff) + ldsw + _i * 8192), 16, 0, 0); } while (0)
; #define PG8_LDA(dst, b, h) do { _Pragma("unroll") for (int m = 0; m < 4; ++m) _Pragma("unroll") for (int k = 0; k < 2; ++k) dst[m][k] = *(const PG8_LAS bf16x8*)(lds + PG8_SA(b, h) + aoff + m * 2048 + k * 1024); } while (0)
; #define PG8_MMA(ai, bj, At, Bt) do { __builtin_amdgcn_s_setprio(1); _Pragma("unroll") for (int m = 0; m < 4; ++m) _Pragma("unroll") for (int n = 0; n < 2; ++n) _Pragma("unroll") for (int k = 0; k < 2; ++k) \
;         acc[ai][bj][m][n] = __builtin_amdgcn_mfma_f32_16x16x32_bf16(Bt[n][k], At[m][k], acc[ai][bj][m][n], 0, 0, 0); __builtin_amdgcn_s_setprio(0); } while (0)
; #define PG8_WAIT_V(n) asm volatile("s_waitcnt vmcnt(" #n ")" ::: "memory")
; #define PG8_WAIT_L(n) asm volatile("s_waitcnt lgkmcnt(" #n ")" ::: "memory")
; #define PG8_BAR __builtin_amdgcn_s_barrier()
; #define PG8_SCHED __builtin_amdgcn_sched_barrier(0)
; template <class Epi, class Sched, bool ALIGN_EPI = false, bool SP2 = false>
; __device__ __forceinline__ void gemm_phase(PG8_LAS unsigned char* lds, const Gemm g, const Sched& S, const Epi& E) {
;     ...
;         for (int t = 0; t < nt; t += 2) {
;     ...
;             PG8_LDA(At, 1, 1); PG8_STAGE(PG8_SB(1, 0), b3, voffB); PG8_STAGE(PG8_SB(1, 1), b3 + hstep, voffB); PG8_STAGE(PG8_SA(1, 0), a3, voffA);
;             PG8_WAIT_V(8); PG8_WAIT_L(0); PG8_BAR; PG8_MMA(1, 0, At, B0); PG8_MMA(1, 1, At, B1); PG8_BAR; PG8_SCHED;
	s_add_i32 s50, s77, s63
	v_lshl_add_u64 v[142:143], v[142:143], 0, s[28:29]
	s_mov_b32 m0, s50
	ds_read_b128 v[206:209], v147 offset:49152
	ds_read_b128 v[210:213], v147 offset:50176
	ds_read_b128 v[214:217], v147 offset:51200
	ds_read_b128 v[218:221], v147 offset:52224
	ds_read_b128 v[222:225], v147 offset:53248
	ds_read_b128 v[226:229], v147 offset:54272
	ds_read_b128 v[230:233], v147 offset:55296
	ds_read_b128 v[234:237], v147 offset:56320
	global_load_lds_dwordx4 v[142:143], off
	s_add_i32 m0, s50, 0x2000
	s_add_u32 s48, s48, 0x100080
	v_lshl_add_u64 v[142:143], v[164:165], 0, s[28:29]
	s_addc_u32 s49, s49, 0
	s_add_i32 s50, s78, s63
	global_load_lds_dwordx4 v[142:143], off
	v_lshl_add_u64 v[142:143], s[48:49], 0, v[2:3]
	s_mov_b32 m0, s50
	s_nop 0
	global_load_lds_dwordx4 v[142:143], off
	v_lshl_add_u64 v[142:143], s[48:49], 0, v[136:137]
	s_add_i32 m0, s50, 0x2000
	s_nop 0
	global_load_lds_dwordx4 v[142:143], off
	v_lshl_add_u64 v[142:143], v[238:239], 0, s[28:29]
	s_mov_b32 m0, s67
	s_nop 0
	global_load_lds_dwordx4 v[142:143], off
	v_lshl_add_u64 v[142:143], v[240:241], 0, s[28:29]
	s_mov_b32 m0, s68
	s_nop 0
	global_load_lds_dwordx4 v[142:143], off
	s_waitcnt vmcnt(8)
	s_waitcnt lgkmcnt(0)
	s_barrier
	s_setprio 1
	s_waitcnt lgkmcnt(0)
	v_mfma_f32_16x16x32_bf16 v[64:67], v[148:151], v[206:209], v[64:67]
	v_mfma_f32_16x16x32_bf16 v[60:63], v[156:159], v[206:209], v[60:63]
	v_mfma_f32_16x16x32_bf16 v[56:59], v[148:151], v[214:217], v[56:59]
	v_mfma_f32_16x16x32_bf16 v[48:51], v[156:159], v[214:217], v[48:51]
	v_mfma_f32_16x16x32_bf16 v[40:43], v[148:151], v[222:225], v[40:43]
	v_mfma_f32_16x16x32_bf16 v[32:35], v[156:159], v[222:225], v[32:35]
	v_mfma_f32_16x16x32_bf16 v[24:27], v[148:151], v[230:233], v[24:27]
	v_mfma_f32_16x16x32_bf16 v[16:19], v[156:159], v[230:233], v[16:19]
	v_mfma_f32_16x16x32_bf16 v[64:67], v[152:155], v[210:213], v[64:67]
	v_mfma_f32_16x16x32_bf16 v[60:63], v[160:163], v[210:213], v[60:63]
	v_mfma_f32_16x16x32_bf16 v[56:59], v[152:155], v[218:221], v[56:59]
	v_mfma_f32_16x16x32_bf16 v[48:51], v[160:163], v[218:221], v[48:51]
	v_mfma_f32_16x16x32_bf16 v[40:43], v[152:155], v[226:229], v[40:43]
	v_mfma_f32_16x16x32_bf16 v[32:35], v[160:163], v[226:229], v[32:35]
	v_mfma_f32_16x16x32_bf16 v[24:27], v[152:155], v[234:237], v[24:27]
	v_mfma_f32_16x16x32_bf16 v[16:19], v[160:163], v[234:237], v[16:19]
	s_setprio 0
	s_setprio 1
	v_mfma_f32_16x16x32_bf16 v[52:55], v[172:175], v[206:209], v[52:55]
	s_add_i32 s76, s76, 2
	s_add_u32 s46, s46, 0x100
	s_addc_u32 s47, s47, 0
	s_add_u32 s74, s74, 0x100
	s_addc_u32 s75, s75, 0
	s_cmp_gt_u32 s76, 61
	v_mfma_f32_16x16x32_bf16 v[44:47], v[180:183], v[206:209], v[44:47]
	v_mfma_f32_16x16x32_bf16 v[36:39], v[172:175], v[214:217], v[36:39]
	v_mfma_f32_16x16x32_bf16 v[28:31], v[180:183], v[214:217], v[28:31]
	v_mfma_f32_16x16x32_bf16 v[20:23], v[172:175], v[222:225], v[20:23]
	v_mfma_f32_16x16x32_bf16 v[12:15], v[180:183], v[222:225], v[12:15]
	v_mfma_f32_16x16x32_bf16 v[8:11], v[172:175], v[230:233], v[8:11]
	v_mfma_f32_16x16x32_bf16 v[4:7], v[180:183], v[230:233], v[4:7]
	v_mfma_f32_16x16x32_bf16 v[52:55], v[176:179], v[210:213], v[52:55]
	v_mfma_f32_16x16x32_bf16 v[44:47], v[184:187], v[210:213], v[44:47]
	v_mfma_f32_16x16x32_bf16 v[36:39], v[176:179], v[218:221], v[36:39]
	v_mfma_f32_16x16x32_bf16 v[28:31], v[184:187], v[218:221], v[28:31]
	v_mfma_f32_16x16x32_bf16 v[20:23], v[176:179], v[226:229], v[20:23]
	v_mfma_f32_16x16x32_bf16 v[12:15], v[184:187], v[226:229], v[12:15]
	v_mfma_f32_16x16x32_bf16 v[8:11], v[176:179], v[234:237], v[8:11]
	v_mfma_f32_16x16x32_bf16 v[4:7], v[184:187], v[234:237], v[4:7]
	s_setprio 0
	s_barrier
	s_cbranch_scc0 .LBB0_360
	s_and_b64 vcc, exec, s[6:7]
	s_cbranch_vccz .LBB0_363
	s_barrier

;     __host__ __device__ bool next(int i, Unit& u) const { if (i) return false; u.pm = pm; u.pn = pn; return true; }
; #define PG8_STAGE(bufoff, gbase, voff) do { _Pragma("unroll") for (int _i = 0; _i < 2; ++_i) \
;         __builtin_amdgcn_global_load_lds((const unsigned*)((const char*)(gbase) + (voff)[_i]), (PG8_LAS unsigned*)(lds + (bufoff) + ldsw + _i * 8192), 16, 0, 0); } while (0)
; #define PG8_LDA(dst, b, h) do { _Pragma("unroll") for (int m = 0; m < 4; ++m) _Pragma("unroll") for (int k = 0; k < 2; ++k) dst[m][k] = *(const PG8_LAS bf16x8*)(lds + PG8_SA(b, h) + aoff + m * 2048 + k * 1024); } while (0)
; #define PG8_LDB(dst, b, h) do { _Pragma("unroll") for (int n = 0; n < 2; ++n) _Pragma("unroll") for (int k = 0; k < 2; ++k) dst[n][k] = *(const PG8_LAS bf16x8*)(lds + PG8_SB(b, h) + boff + n * 2048 + k * 1024); } while (0)
; #define PG8_WAIT_V(n) asm volatile("s_waitcnt vmcnt(" #n ")" ::: "memory")
; #define PG8_WAIT_L(n) asm volatile("s_waitcnt lgkmcnt(" #n ")" ::: "memory")
; template <class Epi, class Sched, bool ALIGN_EPI = false, bool SP2 = false>
; __device__ __forceinline__ void gemm_phase(PG8_LAS unsigned char* lds, const Gemm g, const Sched& S, const Epi& E) {
;     ...
;         const bool has_next = S.next(ui + 1, nxt);
;         const char* nA = has_next ? (const char*)g.A + (size_t)nxt.pm * tstep : cA; const char* nB = has_next ? (const char*)g.Bt + (size_t)nxt.pn * tstep : cB;
;         for (int t = 0; t < nt; t += 2) {
;             const bool last = (t == nt - 2);
;             const char* a1 = cA + (size_t)(t + 1) * kstep;
;             const char* a2 = last ? nA : cA + (size_t)(t + 2) * kstep; const char* b2 = last ? nB : cB + (size_t)(t + 2) * kstep;
;             const char* a3 = a2 + kstep; const char* b3 = b2 + kstep;
;             if (last && has_next) S.a_ready(nxt);
;             if constexpr (SP2) {
;             PG8_LDB(B0, 0, 0); PG8_LDB(B1, 0, 1); PG8_SCHED; PG8_LDA(At, 0, 0); PG8_STAGE(PG8_SA(1, 1), a1 + hstep, voffA);
;             PG8_WAIT_V(8); PG8_WAIT_L(0); PG8_BAR; PG8_MMA(0, 0, At, B0); PG8_MMA(0, 1, At, B1); PG8_BAR; PG8_SCHED;
;             PG8_LDA(At, 0, 1); PG8_STAGE(PG8_SB(0, 0), b2, voffB); PG8_STAGE(PG8_SB(0, 1), b2 + hstep, voffB); PG8_STAGE(PG8_SA(0, 0), a2, voffA);
;             PG8_WAIT_V(8); PG8_WAIT_L(0); PG8_BAR; PG8_MMA(1, 0, At, B0); PG8_MMA(1, 1, At, B1); PG8_BAR; PG8_SCHED;
.LBB0_739:
	s_add_i32 s82, 0, 0x10000
	v_add_u32_e32 v142, s82, v145
	s_add_i32 s84, 0, 0x14000
	ds_read_b128 v[148:151], v142
	ds_read_b128 v[152:155], v142 offset:1024
	ds_read_b128 v[156:159], v142 offset:2048
	ds_read_b128 v[162:165], v142 offset:3072
	v_add_u32_e32 v142, s84, v145
	ds_read_b128 v[172:175], v142
	ds_read_b128 v[176:179], v142 offset:1024
	ds_read_b128 v[180:183], v142 offset:2048
	ds_read_b128 v[184:187], v142 offset:3072
	s_add_u32 s54, s52, 0xfffc0080
	s_addc_u32 s55, s53, -1
	s_cmp_eq_u32 s81, 12
	s_cselect_b32 s57, s43, s55
	s_cselect_b32 s56, s77, s54
	s_cselect_b32 s55, s39, s80
	s_cselect_b32 s54, s78, s79
	v_lshl_add_u64 v[142:143], s[52:53], 0, v[138:139]
	s_add_i32 m0, s47, 0xc000
	ds_read_b128 v[206:209], v147
	ds_read_b128 v[210:213], v147 offset:1024
	ds_read_b128 v[214:217], v147 offset:2048
	ds_read_b128 v[218:221], v147 offset:3072
	ds_read_b128 v[222:225], v147 offset:4096
	ds_read_b128 v[226:229], v147 offset:5120
	ds_read_b128 v[230:233], v147 offset:6144
	ds_read_b128 v[234:237], v147 offset:7168
	global_load_lds_dwordx4 v[142:143], off
	v_lshl_add_u64 v[142:143], s[52:53], 0, v[140:141]
	s_add_i32 m0, s47, 0xe000
	s_nop 0
	global_load_lds_dwordx4 v[142:143], off
	s_waitcnt vmcnt(8)
	s_waitcnt lgkmcnt(0)
	s_barrier
	s_setprio 1
	s_waitcnt lgkmcnt(0)
	v_mfma_f32_16x16x32_bf16 v[128:131], v[148:151], v[206:209], v[128:131]
	v_mfma_f32_16x16x32_bf16 v[124:127], v[156:159], v[206:209], v[124:127]
	v_mfma_f32_16x16x32_bf16 v[120:123], v[148:151], v[214:217], v[120:123]
	v_mfma_f32_16x16x32_bf16 v[112:115], v[156:159], v[214:217], v[112:115]
	v_mfma_f32_16x16x32_bf16 v[104:107], v[148:151], v[222:225], v[104:107]
	v_mfma_f32_16x16x32_bf16 v[96:99], v[156:159], v[222:225], v[96:99]
	v_mfma_f32_16x16x32_bf16 v[88:91], v[148:151], v[230:233], v[88:91]
	v_mfma_f32_16x16x32_bf16 v[80:83], v[156:159], v[230:233], v[80:83]
	v_mfma_f32_16x16x32_bf16 v[128:131], v[152:155], v[210:213], v[128:131]
	v_mfma_f32_16x16x32_bf16 v[124:127], v[162:165], v[210:213], v[124:127]
	v_mfma_f32_16x16x32_bf16 v[120:123], v[152:155], v[218:221], v[120:123]
	v_mfma_f32_16x16x32_bf16 v[112:115], v[162:165], v[218:221], v[112:115]
	v_mfma_f32_16x16x32_bf16 v[104:107], v[152:155], v[226:229], v[104:107]
	v_mfma_f32_16x16x32_bf16 v[96:99], v[162:165], v[226:229], v[96:99]
	v_mfma_f32_16x16x32_bf16 v[88:91], v[152:155], v[234:237], v[88:91]
	v_mfma_f32_16x16x32_bf16 v[80:83], v[162:165], v[234:237], v[80:83]
	s_setprio 0
	s_setprio 1
	v_mfma_f32_16x16x32_bf16 v[116:119], v[172:175], v[206:209], v[116:119]
	v_mfma_f32_16x16x32_bf16 v[108:111], v[180:183], v[206:209], v[108:111]
	v_mfma_f32_16x16x32_bf16 v[100:103], v[172:175], v[214:217], v[100:103]
	v_mfma_f32_16x16x32_bf16 v[92:95], v[180:183], v[214:217], v[92:95]
	v_mfma_f32_16x16x32_bf16 v[84:87], v[172:175], v[222:225], v[84:87]
	v_mfma_f32_16x16x32_bf16 v[76:79], v[180:183], v[222:225], v[76:79]
	v_mfma_f32_16x16x32_bf16 v[72:75], v[172:175], v[230:233], v[72:75]
	v_mfma_f32_16x16x32_bf16 v[68:71], v[180:183], v[230:233], v[68:71]
	v_mfma_f32_16x16x32_bf16 v[116:119], v[176:179], v[210:213], v[116:119]
	v_mfma_f32_16x16x32_bf16 v[108:111], v[184:187], v[210:213], v[108:111]
	v_mfma_f32_16x16x32_bf16 v[100:103], v[176:179], v[218:221], v[100:103]
	v_mfma_f32_16x16x32_bf16 v[92:95], v[184:187], v[218:221], v[92:95]
	v_mfma_f32_16x16x32_bf16 v[84:87], v[176:179], v[226:229], v[84:87]
	v_mfma_f32_16x16x32_bf16 v[76:79], v[184:187], v[226:229], v[76:79]
	v_mfma_f32_16x16x32_bf16 v[72:75], v[176:179], v[234:237], v[72:75]
	v_mfma_f32_16x16x32_bf16 v[68:71], v[184:187], v[234:237], v[68:71]
	s_setprio 0
	s_barrier
	s_add_i32 s82, s82, s61
	v_lshl_add_u64 v[142:143], s[54:55], 0, v[2:3]
	s_mov_b32 m0, s82
	ds_read_b128 v[206:209], v147 offset:16384
	ds_read_b128 v[210:213], v147 offset:17408
	ds_read_b128 v[214:217], v147 offset:18432
	ds_read_b128 v[218:221], v147 offset:19456
	ds_read_b128 v[222:225], v147 offset:20480
	ds_read_b128 v[226:229], v147 offset:21504
	ds_read_b128 v[230:233], v147 offset:22528
	ds_read_b128 v[234:237], v147 offset:23552
	global_load_lds_dwordx4 v[142:143], off
	s_add_i32 m0, s82, 0x2000
	s_add_u32 s82, s54, 0x40000
	v_lshl_add_u64 v[238:239], s[54:55], 0, v[132:133]
	s_addc_u32 s83, s55, 0
	s_add_i32 s84, s84, s61
	global_load_lds_dwordx4 v[238:239], off
	v_lshl_add_u64 v[240:241], s[82:83], 0, v[2:3]
	s_mov_b32 m0, s84
	v_lshl_add_u64 v[242:243], s[56:57], 0, v[134:135]
	global_load_lds_dwordx4 v[240:241], off
	v_lshl_add_u64 v[240:241], s[82:83], 0, v[132:133]
	s_add_i32 m0, s84, 0x2000
	s_nop 0
	global_load_lds_dwordx4 v[240:241], off
	v_lshl_add_u64 v[240:241], s[56:57], 0, v[136:137]
	s_mov_b32 m0, s47
	s_nop 0
	global_load_lds_dwordx4 v[240:241], off
	s_mov_b32 m0, s63
	s_nop 0
	global_load_lds_dwordx4 v[242:243], off
	s_waitcnt vmcnt(8)
	s_waitcnt lgkmcnt(0)
	s_barrier
; #define PG8_STAGE(bufoff, gbase, voff) do { _Pragma("unroll") for (int _i = 0; _i < 2; ++_i) \
;         __builtin_amdgcn_global_load_lds((const unsigned*)((const char*)(gbase) + (voff)[_i]), (PG8_LAS unsigned*)(lds + (bufoff) + ldsw + _i * 8192), 16, 0, 0); } while (0)
; #define PG8_LDA(dst, b, h) do { _Pragma("unroll") for (int m = 0; m < 4; ++m) _Pragma("unroll") for (int k = 0; k < 2; ++k) dst[m][k] = *(const PG8_LAS bf16x8*)(lds + PG8_SA(b, h) + aoff + m * 2048 + k * 1024); } while (0)
; #define PG8_LDB(dst, b, h) do { _Pragma("unroll") for (int n = 0; n < 2; ++n) _Pragma("unroll") for (int k = 0; k < 2; ++k) dst[n][k] = *(const PG8_LAS bf16x8*)(lds + PG8_SB(b, h) + boff + n * 2048 + k * 1024); } while (0)
; #define PG8_MMA(ai, bj, At, Bt) do { __builtin_amdgcn_s_setprio(1); _Pragma("unroll") for (int m = 0; m < 4; ++m) _Pragma("unroll") for (int n = 0; n < 2; ++n) _Pragma("unroll") for (int k = 0; k < 2; ++k) \
;         acc[ai][bj][m][n] = __builtin_amdgcn_mfma_f32_16x16x32_bf16(Bt[n][k], At[m][k], acc[ai][bj][m][n], 0, 0, 0); __builtin_amdgcn_s_setprio(0); } while (0)
; #define PG8_WAIT_V(n) asm volatile("s_waitcnt vmcnt(" #n ")" ::: "memory")
; #define PG8_WAIT_L(n) asm volatile("s_waitcnt lgkmcnt(" #n ")" ::: "memory")
; #define PG8_BAR __builtin_amdgcn_s_barrier()
; #define PG8_SCHED __builtin_amdgcn_sched_barrier(0)
; template <class Epi, class Sched, bool ALIGN_EPI = false, bool SP2 = false>
; __device__ __forceinline__ void gemm_phase(PG8_LAS unsigned char* lds, const Gemm g, const Sched& S, const Epi& E) {
;     ...
;             PG8_WAIT_V(8); PG8_WAIT_L(0); PG8_BAR; PG8_MMA(1, 0, At, B0); PG8_MMA(1, 1, At, B1); PG8_BAR; PG8_SCHED;
;             PG8_LDB(B0, 1, 0); PG8_LDB(B1, 1, 1); PG8_SCHED; PG8_LDA(At, 1, 0); PG8_STAGE(PG8_SA(0, 1), a2 + hstep, voffA);
;             PG8_WAIT_V(8); PG8_WAIT_L(0); PG8_BAR; PG8_MMA(0, 0, At, B0); PG8_MMA(0, 1, At, B1); PG8_BAR; PG8_SCHED;
;             PG8_LDA(At, 1, 1); PG8_STAGE(PG8_SB(1, 0), b3, voffB); PG8_STAGE(PG8_SB(1, 1), b3 + hstep, voffB); PG8_STAGE(PG8_SA(1, 0), a3, voffA);
	s_setprio 1
	s_waitcnt lgkmcnt(0)
	v_mfma_f32_16x16x32_bf16 v[64:67], v[148:151], v[206:209], v[64:67]
	v_mfma_f32_16x16x32_bf16 v[60:63], v[156:159], v[206:209], v[60:63]
	v_mfma_f32_16x16x32_bf16 v[56:59], v[148:151], v[214:217], v[56:59]
	v_mfma_f32_16x16x32_bf16 v[48:51], v[156:159], v[214:217], v[48:51]
	v_mfma_f32_16x16x32_bf16 v[40:43], v[148:151], v[222:225], v[40:43]
	v_mfma_f32_16x16x32_bf16 v[32:35], v[156:159], v[222:225], v[32:35]
	v_mfma_f32_16x16x32_bf16 v[24:27], v[148:151], v[230:233], v[24:27]
	v_mfma_f32_16x16x32_bf16 v[16:19], v[156:159], v[230:233], v[16:19]
	v_mfma_f32_16x16x32_bf16 v[64:67], v[152:155], v[210:213], v[64:67]
	v_mfma_f32_16x16x32_bf16 v[60:63], v[162:165], v[210:213], v[60:63]
	v_mfma_f32_16x16x32_bf16 v[56:59], v[152:155], v[218:221], v[56:59]
	v_mfma_f32_16x16x32_bf16 v[48:51], v[162:165], v[218:221], v[48:51]
	v_mfma_f32_16x16x32_bf16 v[40:43], v[152:155], v[226:229], v[40:43]
	v_mfma_f32_16x16x32_bf16 v[32:35], v[162:165], v[226:229], v[32:35]
	v_mfma_f32_16x16x32_bf16 v[24:27], v[152:155], v[234:237], v[24:27]
	v_mfma_f32_16x16x32_bf16 v[16:19], v[162:165], v[234:237], v[16:19]
	s_setprio 0
	s_setprio 1
	v_mfma_f32_16x16x32_bf16 v[52:55], v[172:175], v[206:209], v[52:55]
	v_mfma_f32_16x16x32_bf16 v[44:47], v[180:183], v[206:209], v[44:47]
	v_mfma_f32_16x16x32_bf16 v[36:39], v[172:175], v[214:217], v[36:39]
	v_mfma_f32_16x16x32_bf16 v[28:31], v[180:183], v[214:217], v[28:31]
	v_mfma_f32_16x16x32_bf16 v[20:23], v[172:175], v[222:225], v[20:23]
	v_mfma_f32_16x16x32_bf16 v[12:15], v[180:183], v[222:225], v[12:15]
	v_mfma_f32_16x16x32_bf16 v[8:11], v[172:175], v[230:233], v[8:11]
	v_mfma_f32_16x16x32_bf16 v[4:7], v[180:183], v[230:233], v[4:7]
	v_mfma_f32_16x16x32_bf16 v[52:55], v[176:179], v[210:213], v[52:55]
	v_mfma_f32_16x16x32_bf16 v[44:47], v[184:187], v[210:213], v[44:47]
	v_mfma_f32_16x16x32_bf16 v[36:39], v[176:179], v[218:221], v[36:39]
	v_mfma_f32_16x16x32_bf16 v[28:31], v[184:187], v[218:221], v[28:31]
	v_mfma_f32_16x16x32_bf16 v[20:23], v[176:179], v[226:229], v[20:23]
	v_mfma_f32_16x16x32_bf16 v[12:15], v[184:187], v[226:229], v[12:15]
	v_mfma_f32_16x16x32_bf16 v[8:11], v[176:179], v[234:237], v[8:11]
	v_mfma_f32_16x16x32_bf16 v[4:7], v[184:187], v[234:237], v[4:7]
	s_setprio 0
	s_barrier
	s_add_i32 s82, 0, 0x18000
	v_add_u32_e32 v161, s82, v145
	s_add_i32 s83, 0, 0x1c000
	ds_read_b128 v[148:151], v161
	ds_read_b128 v[152:155], v161 offset:1024
	ds_read_b128 v[156:159], v161 offset:2048
	ds_read_b128 v[162:165], v161 offset:3072
	v_add_u32_e32 v161, s83, v145
	ds_read_b128 v[172:175], v161
	ds_read_b128 v[176:179], v161 offset:1024
	ds_read_b128 v[180:183], v161 offset:2048
	ds_read_b128 v[184:187], v161 offset:3072
	s_add_u32 s56, s56, 0x40000
	s_addc_u32 s57, s57, 0
	s_mov_b32 m0, s64
	v_lshl_add_u64 v[244:245], s[56:57], 0, v[136:137]
	ds_read_b128 v[206:209], v147 offset:32768
	ds_read_b128 v[210:213], v147 offset:33792
	ds_read_b128 v[214:217], v147 offset:34816
	ds_read_b128 v[218:221], v147 offset:35840
	ds_read_b128 v[222:225], v147 offset:36864
	ds_read_b128 v[226:229], v147 offset:37888
	ds_read_b128 v[230:233], v147 offset:38912
	ds_read_b128 v[234:237], v147 offset:39936
	global_load_lds_dwordx4 v[244:245], off
	v_lshl_add_u64 v[244:245], s[56:57], 0, v[134:135]
	s_mov_b32 m0, s65
	s_nop 0
	global_load_lds_dwordx4 v[244:245], off
	s_waitcnt vmcnt(8)
	s_waitcnt lgkmcnt(0)
	s_barrier
	s_setprio 1
	s_waitcnt lgkmcnt(0)
	v_mfma_f32_16x16x32_bf16 v[128:131], v[148:151], v[206:209], v[128:131]
	v_mfma_f32_16x16x32_bf16 v[124:127], v[156:159], v[206:209], v[124:127]
	v_mfma_f32_16x16x32_bf16 v[120:123], v[148:151], v[214:217], v[120:123]
	v_mfma_f32_16x16x32_bf16 v[112:115], v[156:159], v[214:217], v[112:115]
	v_mfma_f32_16x16x32_bf16 v[104:107], v[148:151], v[222:225], v[104:107]
	v_mfma_f32_16x16x32_bf16 v[96:99], v[156:159], v[222:225], v[96:99]
	v_mfma_f32_16x16x32_bf16 v[88:91], v[148:151], v[230:233], v[88:91]
	v_mfma_f32_16x16x32_bf16 v[80:83], v[156:159], v[230:233], v[80:83]
	v_mfma_f32_16x16x32_bf16 v[128:131], v[152:155], v[210:213], v[128:131]
	v_mfma_f32_16x16x32_bf16 v[124:127], v[162:165], v[210:213], v[124:127]
	v_mfma_f32_16x16x32_bf16 v[120:123], v[152:155], v[218:221], v[120:123]
	v_mfma_f32_16x16x32_bf16 v[112:115], v[162:165], v[218:221], v[112:115]
	v_mfma_f32_16x16x32_bf16 v[104:107], v[152:155], v[226:229], v[104:107]
	v_mfma_f32_16x16x32_bf16 v[96:99], v[162:165], v[226:229], v[96:99]
	v_mfma_f32_16x16x32_bf16 v[88:91], v[152:155], v[234:237], v[88:91]
	v_mfma_f32_16x16x32_bf16 v[80:83], v[162:165], v[234:237], v[80:83]
	s_setprio 0
	s_setprio 1
	v_mfma_f32_16x16x32_bf16 v[116:119], v[172:175], v[206:209], v[116:119]
	v_mfma_f32_16x16x32_bf16 v[108:111], v[180:183], v[206:209], v[108:111]
	v_mfma_f32_16x16x32_bf16 v[100:103], v[172:175], v[214:217], v[100:103]
	v_mfma_f32_16x16x32_bf16 v[92:95], v[180:183], v[214:217], v[92:95]
	v_mfma_f32_16x16x32_bf16 v[84:87], v[172:175], v[222:225], v[84:87]
	v_mfma_f32_16x16x32_bf16 v[76:79], v[180:183], v[222:225], v[76:79]
	v_mfma_f32_16x16x32_bf16 v[72:75], v[172:175], v[230:233], v[72:75]
	v_mfma_f32_16x16x32_bf16 v[68:71], v[180:183], v[230:233], v[68:71]
	v_mfma_f32_16x16x32_bf16 v[116:119], v[176:179], v[210:213], v[116:119]
	v_mfma_f32_16x16x32_bf16 v[108:111], v[184:187], v[210:213], v[108:111]
	v_mfma_f32_16x16x32_bf16 v[100:103], v[176:179], v[218:221], v[100:103]
	v_mfma_f32_16x16x32_bf16 v[92:95], v[184:187], v[218:221], v[92:95]
	v_mfma_f32_16x16x32_bf16 v[84:87], v[176:179], v[226:229], v[84:87]
	v_mfma_f32_16x16x32_bf16 v[76:79], v[184:187], v[226:229], v[76:79]
	v_mfma_f32_16x16x32_bf16 v[72:75], v[176:179], v[234:237], v[72:75]
	v_mfma_f32_16x16x32_bf16 v[68:71], v[184:187], v[234:237], v[68:71]
	s_setprio 0
	s_barrier
; #define PG8_STAGE(bufoff, gbase, voff) do { _Pragma("unroll") for (int _i = 0; _i < 2; ++_i) \
;         __builtin_amdgcn_global_load_lds((const unsigned*)((const char*)(gbase) + (voff)[_i]), (PG8_LAS unsigned*)(lds + (bufoff) + ldsw + _i * 8192), 16, 0, 0); } while (0)
; #define PG8_LDA(dst, b, h) do { _Pragma("unroll") for (int m = 0; m < 4; ++m) _Pragma("unroll") for (int k = 0; k < 2; ++k) dst[m][k] = *(const PG8_LAS bf16x8*)(lds + PG8_SA(b, h) + aoff + m * 2048 + k * 1024); } while (0)
; #define PG8_MMA(ai, bj, At, Bt) do { __builtin_amdgcn_s_setprio(1); _Pragma("unroll") for (int m = 0; m < 4; ++m) _Pragma("unroll") for (int n = 0; n < 2; ++n) _Pragma("unroll") for (int k = 0; k < 2; ++k) \
;         acc[ai][bj][m][n] = __builtin_amdgcn_mfma_f32_16x16x32_bf16(Bt[n][k], At[m][k], acc[ai][bj][m][n], 0, 0, 0); __builtin_amdgcn_s_setprio(0); } while (0)
; #define PG8_WAIT_V(n) asm volatile("s_waitcnt vmcnt(" #n ")" ::: "memory")
; #define PG8_WAIT_L(n) asm volatile("s_waitcnt lgkmcnt(" #n ")" ::: "memory")
; #define PG8_BAR __builtin_amdgcn_s_barrier()
; #define PG8_SCHED __builtin_amdgcn_sched_barrier(0)
; template <class Epi, class Sched, bool ALIGN_EPI = false, bool SP2 = false>
; __device__ __forceinline__ void gemm_phase(PG8_LAS unsigned char* lds, const Gemm g, const Sched& S, const Epi& E) {
;     ...
;         for (int t = 0; t < nt; t += 2) {
;     ...
;             PG8_LDA(At, 1, 1); PG8_STAGE(PG8_SB(1, 0), b3, voffB); PG8_STAGE(PG8_SB(1, 1), b3 + hstep, voffB); PG8_STAGE(PG8_SA(1, 0), a3, voffA);
;             PG8_WAIT_V(8); PG8_WAIT_L(0); PG8_BAR; PG8_MMA(1, 0, At, B0); PG8_MMA(1, 1, At, B1); PG8_BAR; PG8_SCHED;
	s_add_i32 s56, s82, s61
	v_lshl_add_u64 v[142:143], v[142:143], 0, s[28:29]
	s_mov_b32 m0, s56
	ds_read_b128 v[206:209], v147 offset:49152
	ds_read_b128 v[210:213], v147 offset:50176
	ds_read_b128 v[214:217], v147 offset:51200
	ds_read_b128 v[218:221], v147 offset:52224
	ds_read_b128 v[222:225], v147 offset:53248
	ds_read_b128 v[226:229], v147 offset:54272
	ds_read_b128 v[230:233], v147 offset:55296
	ds_read_b128 v[234:237], v147 offset:56320
	global_load_lds_dwordx4 v[142:143], off
	s_add_i32 m0, s56, 0x2000
	s_add_u32 s54, s54, 0x40080
	v_lshl_add_u64 v[142:143], v[238:239], 0, s[28:29]
	s_addc_u32 s55, s55, 0
	s_add_i32 s56, s83, s61
	global_load_lds_dwordx4 v[142:143], off
	v_lshl_add_u64 v[142:143], s[54:55], 0, v[2:3]
	s_mov_b32 m0, s56
	s_nop 0
	global_load_lds_dwordx4 v[142:143], off
	v_lshl_add_u64 v[142:143], s[54:55], 0, v[132:133]
	s_add_i32 m0, s56, 0x2000
	s_nop 0
	global_load_lds_dwordx4 v[142:143], off
	v_lshl_add_u64 v[142:143], v[240:241], 0, s[28:29]
	s_mov_b32 m0, s67
	s_nop 0
	global_load_lds_dwordx4 v[142:143], off
	v_lshl_add_u64 v[142:143], v[242:243], 0, s[28:29]
	s_mov_b32 m0, s68
	s_nop 0
	global_load_lds_dwordx4 v[142:143], off
	s_waitcnt vmcnt(8)
	s_waitcnt lgkmcnt(0)
	s_barrier
	s_setprio 1
	s_waitcnt lgkmcnt(0)
	v_mfma_f32_16x16x32_bf16 v[64:67], v[148:151], v[206:209], v[64:67]
	v_mfma_f32_16x16x32_bf16 v[60:63], v[156:159], v[206:209], v[60:63]
	v_mfma_f32_16x16x32_bf16 v[56:59], v[148:151], v[214:217], v[56:59]
	v_mfma_f32_16x16x32_bf16 v[48:51], v[156:159], v[214:217], v[48:51]
	v_mfma_f32_16x16x32_bf16 v[40:43], v[148:151], v[222:225], v[40:43]
	v_mfma_f32_16x16x32_bf16 v[32:35], v[156:159], v[222:225], v[32:35]
	v_mfma_f32_16x16x32_bf16 v[24:27], v[148:151], v[230:233], v[24:27]
	v_mfma_f32_16x16x32_bf16 v[16:19], v[156:159], v[230:233], v[16:19]
	v_mfma_f32_16x16x32_bf16 v[64:67], v[152:155], v[210:213], v[64:67]
	v_mfma_f32_16x16x32_bf16 v[60:63], v[162:165], v[210:213], v[60:63]
	v_mfma_f32_16x16x32_bf16 v[56:59], v[152:155], v[218:221], v[56:59]
	v_mfma_f32_16x16x32_bf16 v[48:51], v[162:165], v[218:221], v[48:51]
	v_mfma_f32_16x16x32_bf16 v[40:43], v[152:155], v[226:229], v[40:43]
	v_mfma_f32_16x16x32_bf16 v[32:35], v[162:165], v[226:229], v[32:35]
	v_mfma_f32_16x16x32_bf16 v[24:27], v[152:155], v[234:237], v[24:27]
	v_mfma_f32_16x16x32_bf16 v[16:19], v[162:165], v[234:237], v[16:19]
	s_setprio 0
	s_setprio 1
	v_mfma_f32_16x16x32_bf16 v[52:55], v[172:175], v[206:209], v[52:55]
	s_add_i32 s81, s81, 2
	s_add_u32 s52, s52, 0x100
	s_addc_u32 s53, s53, 0
	s_add_u32 s79, s79, 0x100
	s_addc_u32 s80, s80, 0
	s_cmp_gt_u32 s81, 13
	v_mfma_f32_16x16x32_bf16 v[44:47], v[180:183], v[206:209], v[44:47]
	v_mfma_f32_16x16x32_bf16 v[36:39], v[172:175], v[214:217], v[36:39]
	v_mfma_f32_16x16x32_bf16 v[28:31], v[180:183], v[214:217], v[28:31]
	v_mfma_f32_16x16x32_bf16 v[20:23], v[172:175], v[222:225], v[20:23]
	v_mfma_f32_16x16x32_bf16 v[12:15], v[180:183], v[222:225], v[12:15]
	v_mfma_f32_16x16x32_bf16 v[8:11], v[172:175], v[230:233], v[8:11]
	v_mfma_f32_16x16x32_bf16 v[4:7], v[180:183], v[230:233], v[4:7]
	v_mfma_f32_16x16x32_bf16 v[52:55], v[176:179], v[210:213], v[52:55]
	v_mfma_f32_16x16x32_bf16 v[44:47], v[184:187], v[210:213], v[44:47]
	v_mfma_f32_16x16x32_bf16 v[36:39], v[176:179], v[218:221], v[36:39]
	v_mfma_f32_16x16x32_bf16 v[28:31], v[184:187], v[218:221], v[28:31]
	v_mfma_f32_16x16x32_bf16 v[20:23], v[176:179], v[226:229], v[20:23]
	v_mfma_f32_16x16x32_bf16 v[12:15], v[184:187], v[226:229], v[12:15]
	v_mfma_f32_16x16x32_bf16 v[8:11], v[176:179], v[234:237], v[8:11]
	v_mfma_f32_16x16x32_bf16 v[4:7], v[184:187], v[234:237], v[4:7]
	s_setprio 0
	s_barrier
	s_cbranch_scc0 .LBB0_739
	s_and_b64 vcc, exec, s[36:37]
	s_cbranch_vccz .LBB0_742
	s_barrier

;     __host__ __device__ bool next(int i, Unit& u) const { if (i) return false; u.pm = pm; u.pn = pn; return true; }
; #define PG8_STAGE(bufoff, gbase, voff) do { _Pragma("unroll") for (int _i = 0; _i < 2; ++_i) \
;         __builtin_amdgcn_global_load_lds((const unsigned*)((const char*)(gbase) + (voff)[_i]), (PG8_LAS unsigned*)(lds + (bufoff) + ldsw + _i * 8192), 16, 0, 0); } while (0)
; #define PG8_LDA(dst, b, h) do { _Pragma("unroll") for (int m = 0; m < 4; ++m) _Pragma("unroll") for (int k = 0; k < 2; ++k) dst[m][k] = *(const PG8_LAS bf16x8*)(lds + PG8_SA(b, h) + aoff + m * 2048 + k * 1024); } while (0)
; #define PG8_LDB(dst, b, h) do { _Pragma("unroll") for (int n = 0; n < 2; ++n) _Pragma("unroll") for (int k = 0; k < 2; ++k) dst[n][k] = *(const PG8_LAS bf16x8*)(lds + PG8_SB(b, h) + boff + n * 2048 + k * 1024); } while (0)
; #define PG8_WAIT_V(n) asm volatile("s_waitcnt vmcnt(" #n ")" ::: "memory")
; #define PG8_WAIT_L(n) asm volatile("s_waitcnt lgkmcnt(" #n ")" ::: "memory")
; template <class Epi, class Sched, bool ALIGN_EPI = false, bool SP2 = false>
; __device__ __forceinline__ void gemm_phase(PG8_LAS unsigned char* lds, const Gemm g, const Sched& S, const Epi& E) {
;     ...
;         const bool has_next = S.next(ui + 1, nxt);
;         const char* nA = has_next ? (const char*)g.A + (size_t)nxt.pm * tstep : cA; const char* nB = has_next ? (const char*)g.Bt + (size_t)nxt.pn * tstep : cB;
;         for (int t = 0; t < nt; t += 2) {
;             const bool last = (t == nt - 2);
;             const char* a1 = cA + (size_t)(t + 1) * kstep;
;             const char* a2 = last ? nA : cA + (size_t)(t + 2) * kstep; const char* b2 = last ? nB : cB + (size_t)(t + 2) * kstep;
;             const char* a3 = a2 + kstep; const char* b3 = b2 + kstep;
;             if (last && has_next) S.a_ready(nxt);
;             if constexpr (SP2) {
;             PG8_LDB(B0, 0, 0); PG8_LDB(B1, 0, 1); PG8_SCHED; PG8_LDA(At, 0, 0); PG8_STAGE(PG8_SA(1, 1), a1 + hstep, voffA);
;             PG8_WAIT_V(8); PG8_WAIT_L(0); PG8_BAR; PG8_MMA(0, 0, At, B0); PG8_MMA(0, 1, At, B1); PG8_BAR; PG8_SCHED;
;             PG8_LDA(At, 0, 1); PG8_STAGE(PG8_SB(0, 0), b2, voffB); PG8_STAGE(PG8_SB(0, 1), b2 + hstep, voffB); PG8_STAGE(PG8_SA(0, 0), a2, voffA);
;             PG8_WAIT_V(8); PG8_WAIT_L(0); PG8_BAR; PG8_MMA(1, 0, At, B0); PG8_MMA(1, 1, At, B1); PG8_BAR; PG8_SCHED;
.LBB0_765:
	s_add_i32 s93, 0, 0x10000
	v_add_u32_e32 v164, s93, v162
	s_add_i32 s96, 0, 0x14000
	ds_read_b128 v[132:135], v164
	ds_read_b128 v[136:139], v164 offset:1024
	ds_read_b128 v[156:159], v164 offset:2048
	ds_read_b128 v[174:177], v164 offset:3072
	v_add_u32_e32 v164, s96, v162
	ds_read_b128 v[178:181], v164
	ds_read_b128 v[182:185], v164 offset:1024
	ds_read_b128 v[206:209], v164 offset:2048
	ds_read_b128 v[210:213], v164 offset:3072
	s_add_u32 s66, s64, 0xfffe0080
	s_addc_u32 s67, s65, -1
	s_cmp_eq_u32 s92, 4
	s_cselect_b32 s69, s53, s67
	s_cselect_b32 s68, s55, s66
	s_cselect_b32 s67, s51, s91
	s_cselect_b32 s66, s63, s90
	v_lshl_add_u64 v[164:165], s[64:65], 0, v[152:153]
	s_add_i32 m0, s80, 0xc000
	ds_read_b128 v[214:217], v173
	ds_read_b128 v[218:221], v173 offset:1024
	ds_read_b128 v[222:225], v173 offset:2048
	ds_read_b128 v[226:229], v173 offset:3072
	ds_read_b128 v[230:233], v173 offset:4096
	ds_read_b128 v[234:237], v173 offset:5120
	ds_read_b128 v[238:241], v173 offset:6144
	ds_read_b128 v[242:245], v173 offset:7168
	global_load_lds_dwordx4 v[164:165], off
	v_lshl_add_u64 v[164:165], s[64:65], 0, v[154:155]
	s_add_i32 m0, s80, 0xe000
	s_nop 0
	global_load_lds_dwordx4 v[164:165], off
	s_waitcnt vmcnt(8)
	s_waitcnt lgkmcnt(0)
	s_barrier
	s_setprio 1
	s_waitcnt lgkmcnt(0)
	v_mfma_f32_16x16x32_bf16 v[128:131], v[132:135], v[214:217], v[128:131]
	v_mfma_f32_16x16x32_bf16 v[124:127], v[156:159], v[214:217], v[124:127]
	v_mfma_f32_16x16x32_bf16 v[116:119], v[132:135], v[222:225], v[116:119]
	v_mfma_f32_16x16x32_bf16 v[108:111], v[156:159], v[222:225], v[108:111]
	v_mfma_f32_16x16x32_bf16 v[104:107], v[132:135], v[230:233], v[104:107]
	v_mfma_f32_16x16x32_bf16 v[96:99], v[156:159], v[230:233], v[96:99]
	v_mfma_f32_16x16x32_bf16 v[88:91], v[132:135], v[238:241], v[88:91]
	v_mfma_f32_16x16x32_bf16 v[80:83], v[156:159], v[238:241], v[80:83]
	v_mfma_f32_16x16x32_bf16 v[128:131], v[136:139], v[218:221], v[128:131]
	v_mfma_f32_16x16x32_bf16 v[124:127], v[174:177], v[218:221], v[124:127]
	v_mfma_f32_16x16x32_bf16 v[116:119], v[136:139], v[226:229], v[116:119]
	v_mfma_f32_16x16x32_bf16 v[108:111], v[174:177], v[226:229], v[108:111]
	v_mfma_f32_16x16x32_bf16 v[104:107], v[136:139], v[234:237], v[104:107]
	v_mfma_f32_16x16x32_bf16 v[96:99], v[174:177], v[234:237], v[96:99]
	v_mfma_f32_16x16x32_bf16 v[88:91], v[136:139], v[242:245], v[88:91]
	v_mfma_f32_16x16x32_bf16 v[80:83], v[174:177], v[242:245], v[80:83]
	s_setprio 0
	s_setprio 1
	v_mfma_f32_16x16x32_bf16 v[120:123], v[178:181], v[214:217], v[120:123]
	v_mfma_f32_16x16x32_bf16 v[112:115], v[206:209], v[214:217], v[112:115]
	v_mfma_f32_16x16x32_bf16 v[100:103], v[178:181], v[222:225], v[100:103]
	v_mfma_f32_16x16x32_bf16 v[92:95], v[206:209], v[222:225], v[92:95]
	v_mfma_f32_16x16x32_bf16 v[84:87], v[178:181], v[230:233], v[84:87]
	v_mfma_f32_16x16x32_bf16 v[76:79], v[206:209], v[230:233], v[76:79]
	v_mfma_f32_16x16x32_bf16 v[72:75], v[178:181], v[238:241], v[72:75]
	v_mfma_f32_16x16x32_bf16 v[68:71], v[206:209], v[238:241], v[68:71]
	v_mfma_f32_16x16x32_bf16 v[120:123], v[182:185], v[218:221], v[120:123]
	v_mfma_f32_16x16x32_bf16 v[112:115], v[210:213], v[218:221], v[112:115]
	v_mfma_f32_16x16x32_bf16 v[100:103], v[182:185], v[226:229], v[100:103]
	v_mfma_f32_16x16x32_bf16 v[92:95], v[210:213], v[226:229], v[92:95]
	v_mfma_f32_16x16x32_bf16 v[84:87], v[182:185], v[234:237], v[84:87]
	v_mfma_f32_16x16x32_bf16 v[76:79], v[210:213], v[234:237], v[76:79]
	v_mfma_f32_16x16x32_bf16 v[72:75], v[182:185], v[242:245], v[72:75]
	v_mfma_f32_16x16x32_bf16 v[68:71], v[210:213], v[242:245], v[68:71]
	s_setprio 0
	s_barrier
	s_add_i32 s93, s93, s10
	v_lshl_add_u64 v[164:165], s[66:67], 0, v[2:3]
	s_mov_b32 m0, s93
	ds_read_b128 v[214:217], v173 offset:16384
	ds_read_b128 v[218:221], v173 offset:17408
	ds_read_b128 v[222:225], v173 offset:18432
	ds_read_b128 v[226:229], v173 offset:19456
	ds_read_b128 v[230:233], v173 offset:20480
	ds_read_b128 v[234:237], v173 offset:21504
	ds_read_b128 v[238:241], v173 offset:22528
	ds_read_b128 v[242:245], v173 offset:23552
	global_load_lds_dwordx4 v[164:165], off
	s_add_i32 m0, s93, 0x2000
	s_add_u32 s94, s66, 0x20000
	v_lshl_add_u64 v[186:187], s[66:67], 0, v[144:145]
	s_addc_u32 s95, s67, 0
	s_add_i32 s93, s96, s10
	global_load_lds_dwordx4 v[186:187], off
	v_lshl_add_u64 v[246:247], s[94:95], 0, v[2:3]
	s_mov_b32 m0, s93
	v_lshl_add_u64 v[248:249], s[68:69], 0, v[142:143]
	global_load_lds_dwordx4 v[246:247], off
	v_lshl_add_u64 v[246:247], s[94:95], 0, v[144:145]
	s_add_i32 m0, s93, 0x2000
	s_nop 0
	global_load_lds_dwordx4 v[246:247], off
	v_lshl_add_u64 v[246:247], s[68:69], 0, v[140:141]
	s_mov_b32 m0, s80
	s_nop 0
	global_load_lds_dwordx4 v[246:247], off
	s_mov_b32 m0, s81
	s_nop 0
	global_load_lds_dwordx4 v[248:249], off
	s_waitcnt vmcnt(8)
	s_waitcnt lgkmcnt(0)
	s_barrier
; #define PG8_STAGE(bufoff, gbase, voff) do { _Pragma("unroll") for (int _i = 0; _i < 2; ++_i) \
;         __builtin_amdgcn_global_load_lds((const unsigned*)((const char*)(gbase) + (voff)[_i]), (PG8_LAS unsigned*)(lds + (bufoff) + ldsw + _i * 8192), 16, 0, 0); } while (0)
; #define PG8_LDA(dst, b, h) do { _Pragma("unroll") for (int m = 0; m < 4; ++m) _Pragma("unroll") for (int k = 0; k < 2; ++k) dst[m][k] = *(const PG8_LAS bf16x8*)(lds + PG8_SA(b, h) + aoff + m * 2048 + k * 1024); } while (0)
; #define PG8_LDB(dst, b, h) do { _Pragma("unroll") for (int n = 0; n < 2; ++n) _Pragma("unroll") for (int k = 0; k < 2; ++k) dst[n][k] = *(const PG8_LAS bf16x8*)(lds + PG8_SB(b, h) + boff + n * 2048 + k * 1024); } while (0)
; #define PG8_MMA(ai, bj, At, Bt) do { __builtin_amdgcn_s_setprio(1); _Pragma("unroll") for (int m = 0; m < 4; ++m) _Pragma("unroll") for (int n = 0; n < 2; ++n) _Pragma("unroll") for (int k = 0; k < 2; ++k) \
;         acc[ai][bj][m][n] = __builtin_amdgcn_mfma_f32_16x16x32_bf16(Bt[n][k], At[m][k], acc[ai][bj][m][n], 0, 0, 0); __builtin_amdgcn_s_setprio(0); } while (0)
; #define PG8_WAIT_V(n) asm volatile("s_waitcnt vmcnt(" #n ")" ::: "memory")
; #define PG8_WAIT_L(n) asm volatile("s_waitcnt lgkmcnt(" #n ")" ::: "memory")
; #define PG8_BAR __builtin_amdgcn_s_barrier()
; #define PG8_SCHED __builtin_amdgcn_sched_barrier(0)
; template <class Epi, class Sched, bool ALIGN_EPI = false, bool SP2 = false>
; __device__ __forceinline__ void gemm_phase(PG8_LAS unsigned char* lds, const Gemm g, const Sched& S, const Epi& E) {
;     ...
;             PG8_WAIT_V(8); PG8_WAIT_L(0); PG8_BAR; PG8_MMA(1, 0, At, B0); PG8_MMA(1, 1, At, B1); PG8_BAR; PG8_SCHED;
;             PG8_LDB(B0, 1, 0); PG8_LDB(B1, 1, 1); PG8_SCHED; PG8_LDA(At, 1, 0); PG8_STAGE(PG8_SA(0, 1), a2 + hstep, voffA);
;             PG8_WAIT_V(8); PG8_WAIT_L(0); PG8_BAR; PG8_MMA(0, 0, At, B0); PG8_MMA(0, 1, At, B1); PG8_BAR; PG8_SCHED;
;             PG8_LDA(At, 1, 1); PG8_STAGE(PG8_SB(1, 0), b3, voffB); PG8_STAGE(PG8_SB(1, 1), b3 + hstep, voffB); PG8_STAGE(PG8_SA(1, 0), a3, voffA);
	s_setprio 1
	s_waitcnt lgkmcnt(0)
	v_mfma_f32_16x16x32_bf16 v[64:67], v[132:135], v[214:217], v[64:67]
	v_mfma_f32_16x16x32_bf16 v[60:63], v[156:159], v[214:217], v[60:63]
	v_mfma_f32_16x16x32_bf16 v[56:59], v[132:135], v[222:225], v[56:59]
	v_mfma_f32_16x16x32_bf16 v[48:51], v[156:159], v[222:225], v[48:51]
	v_mfma_f32_16x16x32_bf16 v[40:43], v[132:135], v[230:233], v[40:43]
	v_mfma_f32_16x16x32_bf16 v[32:35], v[156:159], v[230:233], v[32:35]
	v_mfma_f32_16x16x32_bf16 v[24:27], v[132:135], v[238:241], v[24:27]
	v_mfma_f32_16x16x32_bf16 v[16:19], v[156:159], v[238:241], v[16:19]
	v_mfma_f32_16x16x32_bf16 v[64:67], v[136:139], v[218:221], v[64:67]
	v_mfma_f32_16x16x32_bf16 v[60:63], v[174:177], v[218:221], v[60:63]
	v_mfma_f32_16x16x32_bf16 v[56:59], v[136:139], v[226:229], v[56:59]
	v_mfma_f32_16x16x32_bf16 v[48:51], v[174:177], v[226:229], v[48:51]
	v_mfma_f32_16x16x32_bf16 v[40:43], v[136:139], v[234:237], v[40:43]
	v_mfma_f32_16x16x32_bf16 v[32:35], v[174:177], v[234:237], v[32:35]
	v_mfma_f32_16x16x32_bf16 v[24:27], v[136:139], v[242:245], v[24:27]
	v_mfma_f32_16x16x32_bf16 v[16:19], v[174:177], v[242:245], v[16:19]
	s_setprio 0
	s_setprio 1
	v_mfma_f32_16x16x32_bf16 v[52:55], v[178:181], v[214:217], v[52:55]
	v_mfma_f32_16x16x32_bf16 v[44:47], v[206:209], v[214:217], v[44:47]
	v_mfma_f32_16x16x32_bf16 v[36:39], v[178:181], v[222:225], v[36:39]
	v_mfma_f32_16x16x32_bf16 v[28:31], v[206:209], v[222:225], v[28:31]
	v_mfma_f32_16x16x32_bf16 v[20:23], v[178:181], v[230:233], v[20:23]
	v_mfma_f32_16x16x32_bf16 v[12:15], v[206:209], v[230:233], v[12:15]
	v_mfma_f32_16x16x32_bf16 v[8:11], v[178:181], v[238:241], v[8:11]
	v_mfma_f32_16x16x32_bf16 v[4:7], v[206:209], v[238:241], v[4:7]
	v_mfma_f32_16x16x32_bf16 v[52:55], v[182:185], v[218:221], v[52:55]
	v_mfma_f32_16x16x32_bf16 v[44:47], v[210:213], v[218:221], v[44:47]
	v_mfma_f32_16x16x32_bf16 v[36:39], v[182:185], v[226:229], v[36:39]
	v_mfma_f32_16x16x32_bf16 v[28:31], v[210:213], v[226:229], v[28:31]
	v_mfma_f32_16x16x32_bf16 v[20:23], v[182:185], v[234:237], v[20:23]
	v_mfma_f32_16x16x32_bf16 v[12:15], v[210:213], v[234:237], v[12:15]
	v_mfma_f32_16x16x32_bf16 v[8:11], v[182:185], v[242:245], v[8:11]
	v_mfma_f32_16x16x32_bf16 v[4:7], v[210:213], v[242:245], v[4:7]
	s_setprio 0
	s_barrier
	s_add_i32 s93, 0, 0x18000
	s_add_i32 s94, 0, 0x1c000
	v_add_u32_e32 v174, s93, v162
	v_add_u32_e32 v194, s94, v162
	ds_read_b128 v[132:135], v174
	ds_read_b128 v[136:139], v174 offset:1024
	ds_read_b128 v[156:159], v174 offset:2048
	ds_read_b128 v[174:177], v174 offset:3072
	ds_read_b128 v[178:181], v194
	ds_read_b128 v[182:185], v194 offset:1024
	ds_read_b128 v[206:209], v194 offset:2048
	ds_read_b128 v[210:213], v194 offset:3072
	s_add_u32 s68, s68, 0x20000
	s_addc_u32 s69, s69, 0
	s_mov_b32 m0, s82
	v_lshl_add_u64 v[194:195], s[68:69], 0, v[140:141]
	ds_read_b128 v[214:217], v173 offset:32768
	ds_read_b128 v[218:221], v173 offset:33792
	ds_read_b128 v[222:225], v173 offset:34816
	ds_read_b128 v[226:229], v173 offset:35840
	ds_read_b128 v[230:233], v173 offset:36864
	ds_read_b128 v[234:237], v173 offset:37888
	ds_read_b128 v[238:241], v173 offset:38912
	ds_read_b128 v[242:245], v173 offset:39936
	global_load_lds_dwordx4 v[194:195], off
	v_lshl_add_u64 v[194:195], s[68:69], 0, v[142:143]
	s_mov_b32 m0, s83
	s_nop 0
	global_load_lds_dwordx4 v[194:195], off
	s_waitcnt vmcnt(8)
	s_waitcnt lgkmcnt(0)
	s_barrier
	s_setprio 1
	s_waitcnt lgkmcnt(0)
	v_mfma_f32_16x16x32_bf16 v[128:131], v[132:135], v[214:217], v[128:131]
	v_mfma_f32_16x16x32_bf16 v[124:127], v[156:159], v[214:217], v[124:127]
	v_mfma_f32_16x16x32_bf16 v[116:119], v[132:135], v[222:225], v[116:119]
	v_mfma_f32_16x16x32_bf16 v[108:111], v[156:159], v[222:225], v[108:111]
	v_mfma_f32_16x16x32_bf16 v[104:107], v[132:135], v[230:233], v[104:107]
	v_mfma_f32_16x16x32_bf16 v[96:99], v[156:159], v[230:233], v[96:99]
	v_mfma_f32_16x16x32_bf16 v[88:91], v[132:135], v[238:241], v[88:91]
	v_mfma_f32_16x16x32_bf16 v[80:83], v[156:159], v[238:241], v[80:83]
	v_mfma_f32_16x16x32_bf16 v[128:131], v[136:139], v[218:221], v[128:131]
	v_mfma_f32_16x16x32_bf16 v[124:127], v[174:177], v[218:221], v[124:127]
	v_mfma_f32_16x16x32_bf16 v[116:119], v[136:139], v[226:229], v[116:119]
	v_mfma_f32_16x16x32_bf16 v[108:111], v[174:177], v[226:229], v[108:111]
	v_mfma_f32_16x16x32_bf16 v[104:107], v[136:139], v[234:237], v[104:107]
	v_mfma_f32_16x16x32_bf16 v[96:99], v[174:177], v[234:237], v[96:99]
	v_mfma_f32_16x16x32_bf16 v[88:91], v[136:139], v[242:245], v[88:91]
	v_mfma_f32_16x16x32_bf16 v[80:83], v[174:177], v[242:245], v[80:83]
	s_setprio 0
	s_setprio 1
	v_mfma_f32_16x16x32_bf16 v[120:123], v[178:181], v[214:217], v[120:123]
	v_mfma_f32_16x16x32_bf16 v[112:115], v[206:209], v[214:217], v[112:115]
	v_mfma_f32_16x16x32_bf16 v[100:103], v[178:181], v[222:225], v[100:103]
	v_mfma_f32_16x16x32_bf16 v[92:95], v[206:209], v[222:225], v[92:95]
	v_mfma_f32_16x16x32_bf16 v[84:87], v[178:181], v[230:233], v[84:87]
	v_mfma_f32_16x16x32_bf16 v[76:79], v[206:209], v[230:233], v[76:79]
	v_mfma_f32_16x16x32_bf16 v[72:75], v[178:181], v[238:241], v[72:75]
	v_mfma_f32_16x16x32_bf16 v[68:71], v[206:209], v[238:241], v[68:71]
	v_mfma_f32_16x16x32_bf16 v[120:123], v[182:185], v[218:221], v[120:123]
	v_mfma_f32_16x16x32_bf16 v[112:115], v[210:213], v[218:221], v[112:115]
	v_mfma_f32_16x16x32_bf16 v[100:103], v[182:185], v[226:229], v[100:103]
	v_mfma_f32_16x16x32_bf16 v[92:95], v[210:213], v[226:229], v[92:95]
	v_mfma_f32_16x16x32_bf16 v[84:87], v[182:185], v[234:237], v[84:87]
	v_mfma_f32_16x16x32_bf16 v[76:79], v[210:213], v[234:237], v[76:79]
	v_mfma_f32_16x16x32_bf16 v[72:75], v[182:185], v[242:245], v[72:75]
	v_mfma_f32_16x16x32_bf16 v[68:71], v[210:213], v[242:245], v[68:71]
	s_setprio 0
	s_barrier
; #define PG8_STAGE(bufoff, gbase, voff) do { _Pragma("unroll") for (int _i = 0; _i < 2; ++_i) \
;         __builtin_amdgcn_global_load_lds((const unsigned*)((const char*)(gbase) + (voff)[_i]), (PG8_LAS unsigned*)(lds + (bufoff) + ldsw + _i * 8192), 16, 0, 0); } while (0)
; #define PG8_LDA(dst, b, h) do { _Pragma("unroll") for (int m = 0; m < 4; ++m) _Pragma("unroll") for (int k = 0; k < 2; ++k) dst[m][k] = *(const PG8_LAS bf16x8*)(lds + PG8_SA(b, h) + aoff + m * 2048 + k * 1024); } while (0)
; #define PG8_MMA(ai, bj, At, Bt) do { __builtin_amdgcn_s_setprio(1); _Pragma("unroll") for (int m = 0; m < 4; ++m) _Pragma("unroll") for (int n = 0; n < 2; ++n) _Pragma("unroll") for (int k = 0; k < 2; ++k) \
;         acc[ai][bj][m][n] = __builtin_amdgcn_mfma_f32_16x16x32_bf16(Bt[n][k], At[m][k], acc[ai][bj][m][n], 0, 0, 0); __builtin_amdgcn_s_setprio(0); } while (0)
; #define PG8_WAIT_V(n) asm volatile("s_waitcnt vmcnt(" #n ")" ::: "memory")
; #define PG8_WAIT_L(n) asm volatile("s_waitcnt lgkmcnt(" #n ")" ::: "memory")
; #define PG8_BAR __builtin_amdgcn_s_barrier()
; #define PG8_SCHED __builtin_amdgcn_sched_barrier(0)
; template <class Epi, class Sched, bool ALIGN_EPI = false, bool SP2 = false>
; __device__ __forceinline__ void gemm_phase(PG8_LAS unsigned char* lds, const Gemm g, const Sched& S, const Epi& E) {
;     ...
;         for (int t = 0; t < nt; t += 2) {
;     ...
;             PG8_LDA(At, 1, 1); PG8_STAGE(PG8_SB(1, 0), b3, voffB); PG8_STAGE(PG8_SB(1, 1), b3 + hstep, voffB); PG8_STAGE(PG8_SA(1, 0), a3, voffA);
;             PG8_WAIT_V(8); PG8_WAIT_L(0); PG8_BAR; PG8_MMA(1, 0, At, B0); PG8_MMA(1, 1, At, B1); PG8_BAR; PG8_SCHED;
	s_add_i32 s68, s93, s10
	v_lshl_add_u64 v[164:165], v[164:165], 0, s[28:29]
	s_mov_b32 m0, s68
	ds_read_b128 v[214:217], v173 offset:49152
	ds_read_b128 v[218:221], v173 offset:50176
	ds_read_b128 v[222:225], v173 offset:51200
	ds_read_b128 v[226:229], v173 offset:52224
	ds_read_b128 v[230:233], v173 offset:53248
	ds_read_b128 v[234:237], v173 offset:54272
	ds_read_b128 v[238:241], v173 offset:55296
	ds_read_b128 v[242:245], v173 offset:56320
	global_load_lds_dwordx4 v[164:165], off
	s_add_i32 m0, s68, 0x2000
	s_add_u32 s66, s66, 0x20080
	v_lshl_add_u64 v[164:165], v[186:187], 0, s[28:29]
	s_addc_u32 s67, s67, 0
	s_add_i32 s68, s94, s10
	global_load_lds_dwordx4 v[164:165], off
	v_lshl_add_u64 v[164:165], s[66:67], 0, v[2:3]
	s_mov_b32 m0, s68
	s_nop 0
	global_load_lds_dwordx4 v[164:165], off
	v_lshl_add_u64 v[164:165], s[66:67], 0, v[144:145]
	s_add_i32 m0, s68, 0x2000
	s_nop 0
	global_load_lds_dwordx4 v[164:165], off
	v_lshl_add_u64 v[164:165], v[246:247], 0, s[28:29]
	s_mov_b32 m0, s84
	s_nop 0
	global_load_lds_dwordx4 v[164:165], off
	v_lshl_add_u64 v[164:165], v[248:249], 0, s[28:29]
	s_mov_b32 m0, s85
	s_nop 0
	global_load_lds_dwordx4 v[164:165], off
	s_waitcnt vmcnt(8)
	s_waitcnt lgkmcnt(0)
	s_barrier
	s_setprio 1
	s_waitcnt lgkmcnt(0)
	v_mfma_f32_16x16x32_bf16 v[64:67], v[132:135], v[214:217], v[64:67]
	v_mfma_f32_16x16x32_bf16 v[60:63], v[156:159], v[214:217], v[60:63]
	v_mfma_f32_16x16x32_bf16 v[56:59], v[132:135], v[222:225], v[56:59]
	v_mfma_f32_16x16x32_bf16 v[48:51], v[156:159], v[222:225], v[48:51]
	v_mfma_f32_16x16x32_bf16 v[40:43], v[132:135], v[230:233], v[40:43]
	v_mfma_f32_16x16x32_bf16 v[32:35], v[156:159], v[230:233], v[32:35]
	v_mfma_f32_16x16x32_bf16 v[24:27], v[132:135], v[238:241], v[24:27]
	v_mfma_f32_16x16x32_bf16 v[16:19], v[156:159], v[238:241], v[16:19]
	v_mfma_f32_16x16x32_bf16 v[64:67], v[136:139], v[218:221], v[64:67]
	v_mfma_f32_16x16x32_bf16 v[60:63], v[174:177], v[218:221], v[60:63]
	v_mfma_f32_16x16x32_bf16 v[56:59], v[136:139], v[226:229], v[56:59]
	v_mfma_f32_16x16x32_bf16 v[48:51], v[174:177], v[226:229], v[48:51]
	v_mfma_f32_16x16x32_bf16 v[40:43], v[136:139], v[234:237], v[40:43]
	v_mfma_f32_16x16x32_bf16 v[32:35], v[174:177], v[234:237], v[32:35]
	v_mfma_f32_16x16x32_bf16 v[24:27], v[136:139], v[242:245], v[24:27]
	v_mfma_f32_16x16x32_bf16 v[16:19], v[174:177], v[242:245], v[16:19]
	s_setprio 0
	s_setprio 1
	v_mfma_f32_16x16x32_bf16 v[52:55], v[178:181], v[214:217], v[52:55]
	s_add_i32 s92, s92, 2
	s_add_u32 s64, s64, 0x100
	s_addc_u32 s65, s65, 0
	s_add_u32 s90, s90, 0x100
	s_addc_u32 s91, s91, 0
	s_cmp_gt_u32 s92, 5
	v_mfma_f32_16x16x32_bf16 v[44:47], v[206:209], v[214:217], v[44:47]
	v_mfma_f32_16x16x32_bf16 v[36:39], v[178:181], v[222:225], v[36:39]
	v_mfma_f32_16x16x32_bf16 v[28:31], v[206:209], v[222:225], v[28:31]
	v_mfma_f32_16x16x32_bf16 v[20:23], v[178:181], v[230:233], v[20:23]
	v_mfma_f32_16x16x32_bf16 v[12:15], v[206:209], v[230:233], v[12:15]
	v_mfma_f32_16x16x32_bf16 v[8:11], v[178:181], v[238:241], v[8:11]
	v_mfma_f32_16x16x32_bf16 v[4:7], v[206:209], v[238:241], v[4:7]
	v_mfma_f32_16x16x32_bf16 v[52:55], v[182:185], v[218:221], v[52:55]
	v_mfma_f32_16x16x32_bf16 v[44:47], v[210:213], v[218:221], v[44:47]
	v_mfma_f32_16x16x32_bf16 v[36:39], v[182:185], v[226:229], v[36:39]
	v_mfma_f32_16x16x32_bf16 v[28:31], v[210:213], v[226:229], v[28:31]
	v_mfma_f32_16x16x32_bf16 v[20:23], v[182:185], v[234:237], v[20:23]
	v_mfma_f32_16x16x32_bf16 v[12:15], v[210:213], v[234:237], v[12:15]
	v_mfma_f32_16x16x32_bf16 v[8:11], v[182:185], v[242:245], v[8:11]
	v_mfma_f32_16x16x32_bf16 v[4:7], v[210:213], v[242:245], v[4:7]
	s_setprio 0
	s_barrier
	s_cbranch_scc0 .LBB0_765
	s_and_b64 vcc, exec, s[42:43]
	s_cbranch_vccz .LBB0_768
	s_barrier

;     __host__ __device__ bool next(int i, Unit& u) const { if (i) return false; u.pm = pm; u.pn = pn; return true; }
; #define PG8_STAGE(bufoff, gbase, voff) do { _Pragma("unroll") for (int _i = 0; _i < 2; ++_i) \
;         __builtin_amdgcn_global_load_lds((const unsigned*)((const char*)(gbase) + (voff)[_i]), (PG8_LAS unsigned*)(lds + (bufoff) + ldsw + _i * 8192), 16, 0, 0); } while (0)
; #define PG8_LDA(dst, b, h) do { _Pragma("unroll") for (int m = 0; m < 4; ++m) _Pragma("unroll") for (int k = 0; k < 2; ++k) dst[m][k] = *(const PG8_LAS bf16x8*)(lds + PG8_SA(b, h) + aoff + m * 2048 + k * 1024); } while (0)
; #define PG8_LDB(dst, b, h) do { _Pragma("unroll") for (int n = 0; n < 2; ++n) _Pragma("unroll") for (int k = 0; k < 2; ++k) dst[n][k] = *(const PG8_LAS bf16x8*)(lds + PG8_SB(b, h) + boff + n * 2048 + k * 1024); } while (0)
; #define PG8_WAIT_V(n) asm volatile("s_waitcnt vmcnt(" #n ")" ::: "memory")
; #define PG8_WAIT_L(n) asm volatile("s_waitcnt lgkmcnt(" #n ")" ::: "memory")
; template <class Epi, class Sched, bool ALIGN_EPI = false, bool SP2 = false>
; __device__ __forceinline__ void gemm_phase(PG8_LAS unsigned char* lds, const Gemm g, const Sched& S, const Epi& E) {
;     ...
;         const bool has_next = S.next(ui + 1, nxt);
;         const char* nA = has_next ? (const char*)g.A + (size_t)nxt.pm * tstep : cA; const char* nB = has_next ? (const char*)g.Bt + (size_t)nxt.pn * tstep : cB;
;         for (int t = 0; t < nt; t += 2) {
;             const bool last = (t == nt - 2);
;             const char* a1 = cA + (size_t)(t + 1) * kstep;
;             const char* a2 = last ? nA : cA + (size_t)(t + 2) * kstep; const char* b2 = last ? nB : cB + (size_t)(t + 2) * kstep;
;             const char* a3 = a2 + kstep; const char* b3 = b2 + kstep;
;             if (last && has_next) S.a_ready(nxt);
;             if constexpr (SP2) {
;             PG8_LDB(B0, 0, 0); PG8_LDB(B1, 0, 1); PG8_SCHED; PG8_LDA(At, 0, 0); PG8_STAGE(PG8_SA(1, 1), a1 + hstep, voffA);
;             PG8_WAIT_V(8); PG8_WAIT_L(0); PG8_BAR; PG8_MMA(0, 0, At, B0); PG8_MMA(0, 1, At, B1); PG8_BAR; PG8_SCHED;
;             PG8_LDA(At, 0, 1); PG8_STAGE(PG8_SB(0, 0), b2, voffB); PG8_STAGE(PG8_SB(0, 1), b2 + hstep, voffB); PG8_STAGE(PG8_SA(0, 0), a2, voffA);
;             PG8_WAIT_V(8); PG8_WAIT_L(0); PG8_BAR; PG8_MMA(1, 0, At, B0); PG8_MMA(1, 1, At, B1); PG8_BAR; PG8_SCHED;
.LBB0_1381:
	s_add_i32 s85, 0, 0x10000
	s_add_i32 s88, 0, 0x14000
	v_add_u32_e32 v144, s85, v209
	v_add_u32_e32 v160, s88, v209
	ds_read_b128 v[132:135], v144
	ds_read_b128 v[136:139], v144 offset:1024
	ds_read_b128 v[140:143], v144 offset:2048
	ds_read_b128 v[144:147], v144 offset:3072
	ds_read_b128 v[148:151], v160
	ds_read_b128 v[152:155], v160 offset:1024
	ds_read_b128 v[156:159], v160 offset:2048
	ds_read_b128 v[160:163], v160 offset:3072
	s_add_u32 s58, s56, 0xfff00080
	s_addc_u32 s59, s57, -1
	s_cmp_eq_u32 s84, 60
	s_cselect_b32 s61, s47, s59
	s_cselect_b32 s60, s80, s58
	s_cselect_b32 s59, s49, s83
	s_cselect_b32 s58, s81, s82
	v_lshl_add_u64 v[164:165], s[56:57], 0, v[174:175]
	s_add_i32 m0, s55, 0xc000
	ds_read_b128 v[178:181], v212
	ds_read_b128 v[182:185], v212 offset:1024
	ds_read_b128 v[214:217], v212 offset:2048
	ds_read_b128 v[218:221], v212 offset:3072
	ds_read_b128 v[222:225], v212 offset:4096
	ds_read_b128 v[226:229], v212 offset:5120
	ds_read_b128 v[230:233], v212 offset:6144
	ds_read_b128 v[234:237], v212 offset:7168
	global_load_lds_dwordx4 v[164:165], off
	v_lshl_add_u64 v[164:165], s[56:57], 0, v[176:177]
	s_add_i32 m0, s55, 0xe000
	s_nop 0
	global_load_lds_dwordx4 v[164:165], off
	s_waitcnt vmcnt(8)
	s_waitcnt lgkmcnt(0)
	s_barrier
	s_setprio 1
	s_waitcnt lgkmcnt(0)
	v_mfma_f32_16x16x32_bf16 v[128:131], v[132:135], v[178:181], v[128:131]
	v_mfma_f32_16x16x32_bf16 v[124:127], v[140:143], v[178:181], v[124:127]
	v_mfma_f32_16x16x32_bf16 v[120:123], v[132:135], v[214:217], v[120:123]
	v_mfma_f32_16x16x32_bf16 v[108:111], v[140:143], v[214:217], v[108:111]
	v_mfma_f32_16x16x32_bf16 v[96:99], v[132:135], v[222:225], v[96:99]
	v_mfma_f32_16x16x32_bf16 v[92:95], v[140:143], v[222:225], v[92:95]
	v_mfma_f32_16x16x32_bf16 v[88:91], v[132:135], v[230:233], v[88:91]
	v_mfma_f32_16x16x32_bf16 v[84:87], v[140:143], v[230:233], v[84:87]
	v_mfma_f32_16x16x32_bf16 v[128:131], v[136:139], v[182:185], v[128:131]
	v_mfma_f32_16x16x32_bf16 v[124:127], v[144:147], v[182:185], v[124:127]
	v_mfma_f32_16x16x32_bf16 v[120:123], v[136:139], v[218:221], v[120:123]
	v_mfma_f32_16x16x32_bf16 v[108:111], v[144:147], v[218:221], v[108:111]
	v_mfma_f32_16x16x32_bf16 v[96:99], v[136:139], v[226:229], v[96:99]
	v_mfma_f32_16x16x32_bf16 v[92:95], v[144:147], v[226:229], v[92:95]
	v_mfma_f32_16x16x32_bf16 v[88:91], v[136:139], v[234:237], v[88:91]
	v_mfma_f32_16x16x32_bf16 v[84:87], v[144:147], v[234:237], v[84:87]
	s_setprio 0
	s_setprio 1
	v_mfma_f32_16x16x32_bf16 v[116:119], v[148:151], v[178:181], v[116:119]
	v_mfma_f32_16x16x32_bf16 v[112:115], v[156:159], v[178:181], v[112:115]
	v_mfma_f32_16x16x32_bf16 v[104:107], v[148:151], v[214:217], v[104:107]
	v_mfma_f32_16x16x32_bf16 v[100:103], v[156:159], v[214:217], v[100:103]
	v_mfma_f32_16x16x32_bf16 v[80:83], v[148:151], v[222:225], v[80:83]
	v_mfma_f32_16x16x32_bf16 v[76:79], v[156:159], v[222:225], v[76:79]
	v_mfma_f32_16x16x32_bf16 v[72:75], v[148:151], v[230:233], v[72:75]
	v_mfma_f32_16x16x32_bf16 v[68:71], v[156:159], v[230:233], v[68:71]
	v_mfma_f32_16x16x32_bf16 v[116:119], v[152:155], v[182:185], v[116:119]
	v_mfma_f32_16x16x32_bf16 v[112:115], v[160:163], v[182:185], v[112:115]
	v_mfma_f32_16x16x32_bf16 v[104:107], v[152:155], v[218:221], v[104:107]
	v_mfma_f32_16x16x32_bf16 v[100:103], v[160:163], v[218:221], v[100:103]
	v_mfma_f32_16x16x32_bf16 v[80:83], v[152:155], v[226:229], v[80:83]
	v_mfma_f32_16x16x32_bf16 v[76:79], v[160:163], v[226:229], v[76:79]
	v_mfma_f32_16x16x32_bf16 v[72:75], v[152:155], v[234:237], v[72:75]
	v_mfma_f32_16x16x32_bf16 v[68:71], v[160:163], v[234:237], v[68:71]
	s_setprio 0
	s_barrier
	s_add_i32 s85, s85, s19
	v_lshl_add_u64 v[164:165], s[58:59], 0, v[2:3]
	s_mov_b32 m0, s85
	ds_read_b128 v[178:181], v212 offset:16384
	ds_read_b128 v[182:185], v212 offset:17408
	ds_read_b128 v[214:217], v212 offset:18432
	ds_read_b128 v[218:221], v212 offset:19456
	ds_read_b128 v[222:225], v212 offset:20480
	ds_read_b128 v[226:229], v212 offset:21504
	ds_read_b128 v[230:233], v212 offset:22528
	ds_read_b128 v[234:237], v212 offset:23552
	global_load_lds_dwordx4 v[164:165], off
	s_add_i32 m0, s85, 0x2000
	s_add_u32 s86, s58, 0x100000
	v_lshl_add_u64 v[186:187], s[58:59], 0, v[172:173]
	s_addc_u32 s87, s59, 0
	s_add_i32 s85, s88, s19
	global_load_lds_dwordx4 v[186:187], off
	v_lshl_add_u64 v[194:195], s[86:87], 0, v[2:3]
	s_mov_b32 m0, s85
	v_lshl_add_u64 v[238:239], s[60:61], 0, v[172:173]
	global_load_lds_dwordx4 v[194:195], off
	v_lshl_add_u64 v[194:195], s[86:87], 0, v[172:173]
	s_add_i32 m0, s85, 0x2000
	s_nop 0
	global_load_lds_dwordx4 v[194:195], off
	v_lshl_add_u64 v[194:195], s[60:61], 0, v[2:3]
	s_mov_b32 m0, s55
	s_nop 0
	global_load_lds_dwordx4 v[194:195], off
	s_mov_b32 m0, s73
	s_nop 0
	global_load_lds_dwordx4 v[238:239], off
	s_waitcnt vmcnt(8)
	s_waitcnt lgkmcnt(0)
	s_barrier
; #define PG8_STAGE(bufoff, gbase, voff) do { _Pragma("unroll") for (int _i = 0; _i < 2; ++_i) \
;         __builtin_amdgcn_global_load_lds((const unsigned*)((const char*)(gbase) + (voff)[_i]), (PG8_LAS unsigned*)(lds + (bufoff) + ldsw + _i * 8192), 16, 0, 0); } while (0)
; #define PG8_LDA(dst, b, h) do { _Pragma("unroll") for (int m = 0; m < 4; ++m) _Pragma("unroll") for (int k = 0; k < 2; ++k) dst[m][k] = *(const PG8_LAS bf16x8*)(lds + PG8_SA(b, h) + aoff + m * 2048 + k * 1024); } while (0)
; #define PG8_LDB(dst, b, h) do { _Pragma("unroll") for (int n = 0; n < 2; ++n) _Pragma("unroll") for (int k = 0; k < 2; ++k) dst[n][k] = *(const PG8_LAS bf16x8*)(lds + PG8_SB(b, h) + boff + n * 2048 + k * 1024); } while (0)
; #define PG8_MMA(ai, bj, At, Bt) do { __builtin_amdgcn_s_setprio(1); _Pragma("unroll") for (int m = 0; m < 4; ++m) _Pragma("unroll") for (int n = 0; n < 2; ++n) _Pragma("unroll") for (int k = 0; k < 2; ++k) \
;         acc[ai][bj][m][n] = __builtin_amdgcn_mfma_f32_16x16x32_bf16(Bt[n][k], At[m][k], acc[ai][bj][m][n], 0, 0, 0); __builtin_amdgcn_s_setprio(0); } while (0)
; #define PG8_BAR __builtin_amdgcn_s_barrier()
; template <class Epi, class Sched, bool ALIGN_EPI = false, bool SP2 = false>
; __device__ __forceinline__ void gemm_phase(PG8_LAS unsigned char* lds, const Gemm g, const Sched& S, const Epi& E) {
;     ...
;             if constexpr (SP2) {
;             PG8_LDB(B0, 0, 0); PG8_LDB(B1, 0, 1); PG8_SCHED; PG8_LDA(At, 0, 0); PG8_STAGE(PG8_SA(1, 1), a1 + hstep, voffA);
;             PG8_WAIT_V(8); PG8_WAIT_L(0); PG8_BAR; PG8_MMA(0, 0, At, B0); PG8_MMA(0, 1, At, B1); PG8_BAR; PG8_SCHED;
;             PG8_LDA(At, 0, 1); PG8_STAGE(PG8_SB(0, 0), b2, voffB); PG8_STAGE(PG8_SB(0, 1), b2 + hstep, voffB); PG8_STAGE(PG8_SA(0, 0), a2, voffA);
;             PG8_WAIT_V(8); PG8_WAIT_L(0); PG8_BAR; PG8_MMA(1, 0, At, B0); PG8_MMA(1, 1, At, B1); PG8_BAR; PG8_SCHED;
;             PG8_LDB(B0, 1, 0); PG8_LDB(B1, 1, 1); PG8_SCHED; PG8_LDA(At, 1, 0); PG8_STAGE(PG8_SA(0, 1), a2 + hstep, voffA);
;             PG8_WAIT_V(8); PG8_WAIT_L(0); PG8_BAR; PG8_MMA(0, 0, At, B0); PG8_MMA(0, 1, At, B1); PG8_BAR; PG8_SCHED;
;             PG8_LDA(At, 1, 1); PG8_STAGE(PG8_SB(1, 0), b3, voffB); PG8_STAGE(PG8_SB(1, 1), b3 + hstep, voffB); PG8_STAGE(PG8_SA(1, 0), a3, voffA);
;             PG8_WAIT_V(8); PG8_WAIT_L(0); PG8_BAR; PG8_MMA(1, 0, At, B0); PG8_MMA(1, 1, At, B1); PG8_BAR; PG8_SCHED;
	s_setprio 1
	s_waitcnt lgkmcnt(0)
	v_mfma_f32_16x16x32_bf16 v[64:67], v[132:135], v[178:181], v[64:67]
	v_mfma_f32_16x16x32_bf16 v[60:63], v[140:143], v[178:181], v[60:63]
	v_mfma_f32_16x16x32_bf16 v[56:59], v[132:135], v[214:217], v[56:59]
	v_mfma_f32_16x16x32_bf16 v[44:47], v[140:143], v[214:217], v[44:47]
	v_mfma_f32_16x16x32_bf16 v[32:35], v[132:135], v[222:225], v[32:35]
	v_mfma_f32_16x16x32_bf16 v[28:31], v[140:143], v[222:225], v[28:31]
	v_mfma_f32_16x16x32_bf16 v[24:27], v[132:135], v[230:233], v[24:27]
	v_mfma_f32_16x16x32_bf16 v[12:15], v[140:143], v[230:233], v[12:15]
	v_mfma_f32_16x16x32_bf16 v[64:67], v[136:139], v[182:185], v[64:67]
	v_mfma_f32_16x16x32_bf16 v[60:63], v[144:147], v[182:185], v[60:63]
	v_mfma_f32_16x16x32_bf16 v[56:59], v[136:139], v[218:221], v[56:59]
	v_mfma_f32_16x16x32_bf16 v[44:47], v[144:147], v[218:221], v[44:47]
	v_mfma_f32_16x16x32_bf16 v[32:35], v[136:139], v[226:229], v[32:35]
	v_mfma_f32_16x16x32_bf16 v[28:31], v[144:147], v[226:229], v[28:31]
	v_mfma_f32_16x16x32_bf16 v[24:27], v[136:139], v[234:237], v[24:27]
	v_mfma_f32_16x16x32_bf16 v[12:15], v[144:147], v[234:237], v[12:15]
	s_setprio 0
	s_setprio 1
	v_mfma_f32_16x16x32_bf16 v[52:55], v[148:151], v[178:181], v[52:55]
	v_mfma_f32_16x16x32_bf16 v[48:51], v[156:159], v[178:181], v[48:51]
	v_mfma_f32_16x16x32_bf16 v[40:43], v[148:151], v[214:217], v[40:43]
	v_mfma_f32_16x16x32_bf16 v[36:39], v[156:159], v[214:217], v[36:39]
	v_mfma_f32_16x16x32_bf16 v[20:23], v[148:151], v[222:225], v[20:23]
	v_mfma_f32_16x16x32_bf16 v[16:19], v[156:159], v[222:225], v[16:19]
	v_mfma_f32_16x16x32_bf16 v[8:11], v[148:151], v[230:233], v[8:11]
	v_mfma_f32_16x16x32_bf16 v[4:7], v[156:159], v[230:233], v[4:7]
	v_mfma_f32_16x16x32_bf16 v[52:55], v[152:155], v[182:185], v[52:55]
	v_mfma_f32_16x16x32_bf16 v[48:51], v[160:163], v[182:185], v[48:51]
	v_mfma_f32_16x16x32_bf16 v[40:43], v[152:155], v[218:221], v[40:43]
	v_mfma_f32_16x16x32_bf16 v[36:39], v[160:163], v[218:221], v[36:39]
	v_mfma_f32_16x16x32_bf16 v[20:23], v[152:155], v[226:229], v[20:23]
	v_mfma_f32_16x16x32_bf16 v[16:19], v[160:163], v[226:229], v[16:19]
	v_mfma_f32_16x16x32_bf16 v[8:11], v[152:155], v[234:237], v[8:11]
	v_mfma_f32_16x16x32_bf16 v[4:7], v[160:163], v[234:237], v[4:7]
	s_setprio 0
	s_barrier
	s_add_i32 s85, 0, 0x18000
	s_add_i32 s86, 0, 0x1c000
	v_add_u32_e32 v144, s85, v209
	v_add_u32_e32 v160, s86, v209
	ds_read_b128 v[132:135], v144
	ds_read_b128 v[136:139], v144 offset:1024
	ds_read_b128 v[140:143], v144 offset:2048
	ds_read_b128 v[144:147], v144 offset:3072
	ds_read_b128 v[148:151], v160
	ds_read_b128 v[152:155], v160 offset:1024
	ds_read_b128 v[156:159], v160 offset:2048
	ds_read_b128 v[160:163], v160 offset:3072
	s_add_u32 s60, s60, 0x100000
	s_addc_u32 s61, s61, 0
	s_mov_b32 m0, s74
	v_lshl_add_u64 v[240:241], s[60:61], 0, v[2:3]
	ds_read_b128 v[178:181], v212 offset:32768
	ds_read_b128 v[182:185], v212 offset:33792
	ds_read_b128 v[214:217], v212 offset:34816
	ds_read_b128 v[218:221], v212 offset:35840
	ds_read_b128 v[222:225], v212 offset:36864
	ds_read_b128 v[226:229], v212 offset:37888
	ds_read_b128 v[230:233], v212 offset:38912
	ds_read_b128 v[234:237], v212 offset:39936
	global_load_lds_dwordx4 v[240:241], off
	v_lshl_add_u64 v[240:241], s[60:61], 0, v[172:173]
	s_mov_b32 m0, s75
	s_nop 0
	global_load_lds_dwordx4 v[240:241], off
	s_waitcnt vmcnt(8)
	s_waitcnt lgkmcnt(0)
	s_barrier
	s_setprio 1
	s_waitcnt lgkmcnt(0)
	v_mfma_f32_16x16x32_bf16 v[128:131], v[132:135], v[178:181], v[128:131]
	v_mfma_f32_16x16x32_bf16 v[124:127], v[140:143], v[178:181], v[124:127]
	v_mfma_f32_16x16x32_bf16 v[120:123], v[132:135], v[214:217], v[120:123]
	v_mfma_f32_16x16x32_bf16 v[108:111], v[140:143], v[214:217], v[108:111]
	v_mfma_f32_16x16x32_bf16 v[96:99], v[132:135], v[222:225], v[96:99]
	v_mfma_f32_16x16x32_bf16 v[92:95], v[140:143], v[222:225], v[92:95]
	v_mfma_f32_16x16x32_bf16 v[88:91], v[132:135], v[230:233], v[88:91]
	v_mfma_f32_16x16x32_bf16 v[84:87], v[140:143], v[230:233], v[84:87]
	v_mfma_f32_16x16x32_bf16 v[128:131], v[136:139], v[182:185], v[128:131]
	v_mfma_f32_16x16x32_bf16 v[124:127], v[144:147], v[182:185], v[124:127]
	v_mfma_f32_16x16x32_bf16 v[120:123], v[136:139], v[218:221], v[120:123]
	v_mfma_f32_16x16x32_bf16 v[108:111], v[144:147], v[218:221], v[108:111]
	v_mfma_f32_16x16x32_bf16 v[96:99], v[136:139], v[226:229], v[96:99]
	v_mfma_f32_16x16x32_bf16 v[92:95], v[144:147], v[226:229], v[92:95]
	v_mfma_f32_16x16x32_bf16 v[88:91], v[136:139], v[234:237], v[88:91]
	v_mfma_f32_16x16x32_bf16 v[84:87], v[144:147], v[234:237], v[84:87]
	s_setprio 0
	s_setprio 1
	v_mfma_f32_16x16x32_bf16 v[116:119], v[148:151], v[178:181], v[116:119]
	v_mfma_f32_16x16x32_bf16 v[112:115], v[156:159], v[178:181], v[112:115]
	v_mfma_f32_16x16x32_bf16 v[104:107], v[148:151], v[214:217], v[104:107]
	v_mfma_f32_16x16x32_bf16 v[100:103], v[156:159], v[214:217], v[100:103]
	v_mfma_f32_16x16x32_bf16 v[80:83], v[148:151], v[222:225], v[80:83]
	v_mfma_f32_16x16x32_bf16 v[76:79], v[156:159], v[222:225], v[76:79]
	v_mfma_f32_16x16x32_bf16 v[72:75], v[148:151], v[230:233], v[72:75]
	v_mfma_f32_16x16x32_bf16 v[68:71], v[156:159], v[230:233], v[68:71]
	v_mfma_f32_16x16x32_bf16 v[116:119], v[152:155], v[182:185], v[116:119]
	v_mfma_f32_16x16x32_bf16 v[112:115], v[160:163], v[182:185], v[112:115]
	v_mfma_f32_16x16x32_bf16 v[104:107], v[152:155], v[218:221], v[104:107]
	v_mfma_f32_16x16x32_bf16 v[100:103], v[160:163], v[218:221], v[100:103]
	v_mfma_f32_16x16x32_bf16 v[80:83], v[152:155], v[226:229], v[80:83]
	v_mfma_f32_16x16x32_bf16 v[76:79], v[160:163], v[226:229], v[76:79]
	v_mfma_f32_16x16x32_bf16 v[72:75], v[152:155], v[234:237], v[72:75]
	v_mfma_f32_16x16x32_bf16 v[68:71], v[160:163], v[234:237], v[68:71]
	s_setprio 0
	s_barrier
; #define PG8_STAGE(bufoff, gbase, voff) do { _Pragma("unroll") for (int _i = 0; _i < 2; ++_i) \
;         __builtin_amdgcn_global_load_lds((const unsigned*)((const char*)(gbase) + (voff)[_i]), (PG8_LAS unsigned*)(lds + (bufoff) + ldsw + _i * 8192), 16, 0, 0); } while (0)
; #define PG8_LDA(dst, b, h) do { _Pragma("unroll") for (int m = 0; m < 4; ++m) _Pragma("unroll") for (int k = 0; k < 2; ++k) dst[m][k] = *(const PG8_LAS bf16x8*)(lds + PG8_SA(b, h) + aoff + m * 2048 + k * 1024); } while (0)
; #define PG8_LDB(dst, b, h) do { _Pragma("unroll") for (int n = 0; n < 2; ++n) _Pragma("unroll") for (int k = 0; k < 2; ++k) dst[n][k] = *(const PG8_LAS bf16x8*)(lds + PG8_SB(b, h) + boff + n * 2048 + k * 1024); } while (0)
; template <class Epi, class Sched, bool ALIGN_EPI = false, bool SP2 = false>
; __device__ __forceinline__ void gemm_phase(PG8_LAS unsigned char* lds, const Gemm g, const Sched& S, const Epi& E) {
;     ...
;         for (int t = 0; t < nt; t += 2) {
;             const bool last = (t == nt - 2);
;             const char* a1 = cA + (size_t)(t + 1) * kstep;
;             const char* a2 = last ? nA : cA + (size_t)(t + 2) * kstep; const char* b2 = last ? nB : cB + (size_t)(t + 2) * kstep;
;             const char* a3 = a2 + kstep; const char* b3 = b2 + kstep;
;             if (last && has_next) S.a_ready(nxt);
;             if constexpr (SP2) {
;             PG8_LDB(B0, 0, 0); PG8_LDB(B1, 0, 1); PG8_SCHED; PG8_LDA(At, 0, 0); PG8_STAGE(PG8_SA(1, 1), a1 + hstep, voffA);
;             PG8_WAIT_V(8); PG8_WAIT_L(0); PG8_BAR; PG8_MMA(0, 0, At, B0); PG8_MMA(0, 1, At, B1); PG8_BAR; PG8_SCHED;
;             PG8_LDA(At, 0, 1); PG8_STAGE(PG8_SB(0, 0), b2, voffB); PG8_STAGE(PG8_SB(0, 1), b2 + hstep, voffB); PG8_STAGE(PG8_SA(0, 0), a2, voffA);
;             PG8_WAIT_V(8); PG8_WAIT_L(0); PG8_BAR; PG8_MMA(1, 0, At, B0); PG8_MMA(1, 1, At, B1); PG8_BAR; PG8_SCHED;
;             PG8_LDB(B0, 1, 0); PG8_LDB(B1, 1, 1); PG8_SCHED; PG8_LDA(At, 1, 0); PG8_STAGE(PG8_SA(0, 1), a2 + hstep, voffA);
;             PG8_WAIT_V(8); PG8_WAIT_L(0); PG8_BAR; PG8_MMA(0, 0, At, B0); PG8_MMA(0, 1, At, B1); PG8_BAR; PG8_SCHED;
;             PG8_LDA(At, 1, 1); PG8_STAGE(PG8_SB(1, 0), b3, voffB); PG8_STAGE(PG8_SB(1, 1), b3 + hstep, voffB); PG8_STAGE(PG8_SA(1, 0), a3, voffA);
;             PG8_WAIT_V(8); PG8_WAIT_L(0); PG8_BAR; PG8_MMA(1, 0, At, B0); PG8_MMA(1, 1, At, B1); PG8_BAR; PG8_SCHED;
	s_add_i32 s60, s85, s19
	v_lshl_add_u64 v[164:165], v[164:165], 0, s[28:29]
	s_mov_b32 m0, s60
	ds_read_b128 v[178:181], v212 offset:49152
	ds_read_b128 v[182:185], v212 offset:50176
	ds_read_b128 v[214:217], v212 offset:51200
	ds_read_b128 v[218:221], v212 offset:52224
	ds_read_b128 v[222:225], v212 offset:53248
	ds_read_b128 v[226:229], v212 offset:54272
	ds_read_b128 v[230:233], v212 offset:55296
	ds_read_b128 v[234:237], v212 offset:56320
	global_load_lds_dwordx4 v[164:165], off
	s_add_i32 m0, s60, 0x2000
	s_add_u32 s58, s58, 0x100080
	v_lshl_add_u64 v[164:165], v[186:187], 0, s[28:29]
	s_addc_u32 s59, s59, 0
	s_add_i32 s60, s86, s19
	global_load_lds_dwordx4 v[164:165], off
	v_lshl_add_u64 v[164:165], s[58:59], 0, v[2:3]
	s_mov_b32 m0, s60
	s_nop 0
	global_load_lds_dwordx4 v[164:165], off
	v_lshl_add_u64 v[164:165], s[58:59], 0, v[172:173]
	s_add_i32 m0, s60, 0x2000
	s_nop 0
	global_load_lds_dwordx4 v[164:165], off
	v_lshl_add_u64 v[164:165], v[194:195], 0, s[28:29]
	s_mov_b32 m0, s77
	s_nop 0
	global_load_lds_dwordx4 v[164:165], off
	v_lshl_add_u64 v[164:165], v[238:239], 0, s[28:29]
	s_mov_b32 m0, s78
	s_nop 0
	global_load_lds_dwordx4 v[164:165], off
	s_waitcnt vmcnt(8)
	s_waitcnt lgkmcnt(0)
	s_barrier
	s_setprio 1
	s_waitcnt lgkmcnt(0)
	v_mfma_f32_16x16x32_bf16 v[64:67], v[132:135], v[178:181], v[64:67]
	v_mfma_f32_16x16x32_bf16 v[60:63], v[140:143], v[178:181], v[60:63]
	v_mfma_f32_16x16x32_bf16 v[56:59], v[132:135], v[214:217], v[56:59]
	v_mfma_f32_16x16x32_bf16 v[44:47], v[140:143], v[214:217], v[44:47]
	v_mfma_f32_16x16x32_bf16 v[32:35], v[132:135], v[222:225], v[32:35]
	v_mfma_f32_16x16x32_bf16 v[28:31], v[140:143], v[222:225], v[28:31]
	v_mfma_f32_16x16x32_bf16 v[24:27], v[132:135], v[230:233], v[24:27]
	v_mfma_f32_16x16x32_bf16 v[12:15], v[140:143], v[230:233], v[12:15]
	v_mfma_f32_16x16x32_bf16 v[64:67], v[136:139], v[182:185], v[64:67]
	v_mfma_f32_16x16x32_bf16 v[60:63], v[144:147], v[182:185], v[60:63]
	v_mfma_f32_16x16x32_bf16 v[56:59], v[136:139], v[218:221], v[56:59]
	v_mfma_f32_16x16x32_bf16 v[44:47], v[144:147], v[218:221], v[44:47]
	v_mfma_f32_16x16x32_bf16 v[32:35], v[136:139], v[226:229], v[32:35]
	v_mfma_f32_16x16x32_bf16 v[28:31], v[144:147], v[226:229], v[28:31]
	v_mfma_f32_16x16x32_bf16 v[24:27], v[136:139], v[234:237], v[24:27]
	v_mfma_f32_16x16x32_bf16 v[12:15], v[144:147], v[234:237], v[12:15]
	s_setprio 0
	s_setprio 1
	v_mfma_f32_16x16x32_bf16 v[52:55], v[148:151], v[178:181], v[52:55]
	s_add_i32 s84, s84, 2
	s_add_u32 s56, s56, 0x100
	s_addc_u32 s57, s57, 0
	s_add_u32 s82, s82, 0x100
	s_addc_u32 s83, s83, 0
	s_cmp_gt_u32 s84, 61
	v_mfma_f32_16x16x32_bf16 v[48:51], v[156:159], v[178:181], v[48:51]
	v_mfma_f32_16x16x32_bf16 v[40:43], v[148:151], v[214:217], v[40:43]
	v_mfma_f32_16x16x32_bf16 v[36:39], v[156:159], v[214:217], v[36:39]
	v_mfma_f32_16x16x32_bf16 v[20:23], v[148:151], v[222:225], v[20:23]
	v_mfma_f32_16x16x32_bf16 v[16:19], v[156:159], v[222:225], v[16:19]
	v_mfma_f32_16x16x32_bf16 v[8:11], v[148:151], v[230:233], v[8:11]
	v_mfma_f32_16x16x32_bf16 v[4:7], v[156:159], v[230:233], v[4:7]
	v_mfma_f32_16x16x32_bf16 v[52:55], v[152:155], v[182:185], v[52:55]
	v_mfma_f32_16x16x32_bf16 v[48:51], v[160:163], v[182:185], v[48:51]
	v_mfma_f32_16x16x32_bf16 v[40:43], v[152:155], v[218:221], v[40:43]
	v_mfma_f32_16x16x32_bf16 v[36:39], v[160:163], v[218:221], v[36:39]
	v_mfma_f32_16x16x32_bf16 v[20:23], v[152:155], v[226:229], v[20:23]
	v_mfma_f32_16x16x32_bf16 v[16:19], v[160:163], v[226:229], v[16:19]
	v_mfma_f32_16x16x32_bf16 v[8:11], v[152:155], v[234:237], v[8:11]
	v_mfma_f32_16x16x32_bf16 v[4:7], v[160:163], v[234:237], v[4:7]
	s_setprio 0
	s_barrier
	s_cbranch_scc0 .LBB0_1381
	s_and_b64 vcc, exec, s[42:43]
	s_cbranch_vccz .LBB0_1384
	s_barrier
